# w1 as 256x128-tile GEMM: weights stored fragment-blocked by a new converter, B fragments read straight to VGPRs, A via 2-stage LDS ring and register fragment ring
# speedup vs baseline: 1.0796x; 1.0063x over previous
.LBB0_39:
.LBB0_40:
	v_readlane_b32 s4, v239, 5
	v_readlane_b32 s5, v239, 6
	s_andn2_b64 vcc, exec, s[4:5]
	s_cbranch_vccnz .LBB0_45
	s_load_dwordx2 s[4:5], s[0:1], 0x130
	v_and_b32_e32 v0, 63, v133
	v_lshrrev_b32_e32 v131, 6, v133
	v_lshrrev_b32_e32 v195, 2, v0
	v_readfirstlane_b32 s15, v131
	v_mul_u32_u24_e32 v218, 0x800, v195
	v_and_b32_e32 v195, 3, v0
	v_lshlrev_b32_e32 v195, 4, v195
	v_lshrrev_b32_e32 v131, 5, v0
	v_lshlrev_b32_e32 v131, 5, v131
	v_xor_b32_e32 v195, v195, v131
	v_add_u32_e32 v218, v218, v195
	v_and_b32_e32 v195, 15, v0
	v_lshrrev_b32_e32 v131, 4, v0
	v_lshlrev_b32_e32 v216, 6, v195
	v_lshl_or_b32 v216, v131, 4, v216
	v_and_b32_e32 v219, 8, v0
	v_lshlrev_b32_e32 v219, 2, v219
	v_xor_b32_e32 v216, v216, v219
	v_mul_u32_u24_e32 v219, 0x2000, v195
	v_lshl_or_b32 v219, v131, 3, v219
	v_lshlrev_b32_e32 v222, 4, v0
	s_waitcnt lgkmcnt(0)
	s_add_u32 s18, s4, 0x2b27800
	s_addc_u32 s19, s5, 0
	s_add_u32 s20, s4, 0x1b27800
	s_addc_u32 s21, s5, 0
	s_add_u32 s24, s4, 0x4b27800
	s_addc_u32 s25, s5, 0
	s_lshl_b32 s22, s15, 13
	s_mov_b32 s12, s79
	s_cmp_ge_u32 s12, 256
	s_cbranch_scc1 .Lg256b_w1_done
	s_lshr_b32 s3, s12, 6
	s_lshl_b32 s3, s3, 3
	s_add_u32 s3, s3, s65
	s_lshr_b32 s17, s3, 2
	s_and_b32 s3, s3, 3
	s_lshl_b32 s17, s17, 3
	s_bfe_u32 s23, s12, 0x30003
	s_add_u32 s13, s17, s23
	s_lshl_b32 s3, s3, 3
	s_and_b32 s23, s12, 7
	s_add_u32 s14, s3, s23
	s_lshl_b32 s13, s13, 8
	s_lshl_b32 s14, s14, 7
	s_lshl_b32 s3, s15, 6
	s_add_u32 s17, s3, s13
	s_mul_i32 s17, s17, 0x800
	s_add_u32 s6, s18, s17
	s_addc_u32 s7, s19, 0
	s_lshr_b32 s3, s14, 4
	s_lshl_b32 s17, s15, 1
	s_add_u32 s3, s3, s17
	s_mul_i32 s17, s3, 0x8000
	s_add_u32 s8, s20, s17
	s_addc_u32 s9, s21, 0
	s_barrier
	v_mov_b32_e32 v217, v218
	v_mov_b32_e32 v220, v222
	v_add_u32_e32 v221, 0x8000, v222
	s_add_u32 m0, s22, 0x0
	v_mov_b32_e32 v223, v217
	global_load_lds_dwordx4 v223, s[6:7]
	s_add_u32 m0, s22, 0x400
	v_add_u32_e32 v224, 0x40, v217
	global_load_lds_dwordx4 v224, s[6:7]
	s_add_u32 m0, s22, 0x800
	v_add_u32_e32 v223, 0x8000, v217
	global_load_lds_dwordx4 v223, s[6:7]
	s_add_u32 m0, s22, 0xc00
	v_add_u32_e32 v224, 0x8040, v217
	global_load_lds_dwordx4 v224, s[6:7]
	s_add_u32 m0, s22, 0x1000
	v_add_u32_e32 v223, 0x10000, v217
	global_load_lds_dwordx4 v223, s[6:7]
	s_add_u32 m0, s22, 0x1400
	v_add_u32_e32 v224, 0x10040, v217
	global_load_lds_dwordx4 v224, s[6:7]
	s_add_u32 m0, s22, 0x1800
	v_add_u32_e32 v223, 0x18000, v217
	global_load_lds_dwordx4 v223, s[6:7]
	s_add_u32 m0, s22, 0x1c00
	v_add_u32_e32 v224, 0x18040, v217
	global_load_lds_dwordx4 v224, s[6:7]
	v_add_u32_e32 v217, 0x80, v217
	s_add_u32 m0, s22, 0x8000
	v_mov_b32_e32 v223, v217
	global_load_lds_dwordx4 v223, s[6:7]
	s_add_u32 m0, s22, 0x8400
	v_add_u32_e32 v224, 0x40, v217
	global_load_lds_dwordx4 v224, s[6:7]
	s_add_u32 m0, s22, 0x8800
	v_add_u32_e32 v223, 0x8000, v217
	global_load_lds_dwordx4 v223, s[6:7]
	s_add_u32 m0, s22, 0x8c00
	v_add_u32_e32 v224, 0x8040, v217
	global_load_lds_dwordx4 v224, s[6:7]
	s_add_u32 m0, s22, 0x9000
	v_add_u32_e32 v223, 0x10000, v217
	global_load_lds_dwordx4 v223, s[6:7]
	s_add_u32 m0, s22, 0x9400
	v_add_u32_e32 v224, 0x10040, v217
	global_load_lds_dwordx4 v224, s[6:7]
	s_add_u32 m0, s22, 0x9800
	v_add_u32_e32 v223, 0x18000, v217
	global_load_lds_dwordx4 v223, s[6:7]
	s_add_u32 m0, s22, 0x9c00
	v_add_u32_e32 v224, 0x18040, v217
	global_load_lds_dwordx4 v224, s[6:7]
	v_add_u32_e32 v217, 0x80, v217
	global_load_dwordx4 v[166:169], v220, s[8:9]
	global_load_dwordx4 v[170:173], v220, s[8:9] offset:1024
	global_load_dwordx4 v[174:177], v221, s[8:9]
	global_load_dwordx4 v[178:181], v221, s[8:9] offset:1024
	v_add_u32_e32 v220, 0x800, v220
	v_add_u32_e32 v221, 0x800, v221
	s_waitcnt vmcnt(0)
	s_barrier
	ds_read_b128 v[134:137], v216
	ds_read_b128 v[138:141], v216 offset:2048
	ds_read_b128 v[142:145], v216 offset:4096
	ds_read_b128 v[146:149], v216 offset:6144
	ds_read_b128 v[150:153], v216 offset:8192
	ds_read_b128 v[154:157], v216 offset:10240
.Lg256b_w1_tile:
	s_mul_i32 s17, s13, 0x2000
	s_lshl_b32 s3, s15, 5
	s_add_u32 s3, s3, s14
	s_mul_i32 s3, s3, 2
	s_add_u32 s17, s17, s3
	s_add_u32 s10, s24, s17
	s_addc_u32 s11, s25, 0
	ds_read_b128 v[158:161], v216 offset:12288
	s_waitcnt vmcnt(40) lgkmcnt(6)
	v_mfma_f32_16x16x32_bf16 v[2:5], v[166:169], v[134:137], 0
	global_load_dwordx4 v[196:199], v220, s[8:9]
	v_mfma_f32_16x16x32_bf16 v[6:9], v[174:177], v[134:137], 0
	global_load_dwordx4 v[200:203], v220, s[8:9] offset:1024
	ds_read_b128 v[162:165], v216 offset:14336
	s_waitcnt lgkmcnt(6)
	v_mfma_f32_16x16x32_bf16 v[10:13], v[166:169], v[138:141], 0
	global_load_dwordx4 v[204:207], v221, s[8:9]
	v_mfma_f32_16x16x32_bf16 v[14:17], v[174:177], v[138:141], 0
	global_load_dwordx4 v[212:215], v221, s[8:9] offset:1024
	ds_read_b128 v[134:137], v216 offset:16384
	s_waitcnt lgkmcnt(6)
	v_mfma_f32_16x16x32_bf16 v[18:21], v[166:169], v[142:145], 0
	v_mfma_f32_16x16x32_bf16 v[22:25], v[174:177], v[142:145], 0
	ds_read_b128 v[138:141], v216 offset:18432
	s_waitcnt lgkmcnt(6)
	v_mfma_f32_16x16x32_bf16 v[26:29], v[166:169], v[146:149], 0
	v_mfma_f32_16x16x32_bf16 v[30:33], v[174:177], v[146:149], 0
	ds_read_b128 v[142:145], v216 offset:20480
	s_waitcnt lgkmcnt(6)
	v_mfma_f32_16x16x32_bf16 v[34:37], v[166:169], v[150:153], 0
	v_mfma_f32_16x16x32_bf16 v[38:41], v[174:177], v[150:153], 0
	ds_read_b128 v[146:149], v216 offset:22528
	s_waitcnt lgkmcnt(6)
	v_mfma_f32_16x16x32_bf16 v[42:45], v[166:169], v[154:157], 0
	v_mfma_f32_16x16x32_bf16 v[46:49], v[174:177], v[154:157], 0
	ds_read_b128 v[150:153], v216 offset:24576
	s_waitcnt lgkmcnt(6)
	v_mfma_f32_16x16x32_bf16 v[50:53], v[166:169], v[158:161], 0
	v_mfma_f32_16x16x32_bf16 v[54:57], v[174:177], v[158:161], 0
	ds_read_b128 v[154:157], v216 offset:26624
	s_waitcnt lgkmcnt(6)
	v_mfma_f32_16x16x32_bf16 v[58:61], v[166:169], v[162:165], 0
	v_mfma_f32_16x16x32_bf16 v[62:65], v[174:177], v[162:165], 0
	ds_read_b128 v[158:161], v216 offset:28672
	s_waitcnt lgkmcnt(6)
	v_mfma_f32_16x16x32_bf16 v[66:69], v[166:169], v[134:137], 0
	v_mfma_f32_16x16x32_bf16 v[70:73], v[174:177], v[134:137], 0
	ds_read_b128 v[162:165], v216 offset:30720
	s_waitcnt lgkmcnt(6)
	v_mfma_f32_16x16x32_bf16 v[74:77], v[166:169], v[138:141], 0
	v_mfma_f32_16x16x32_bf16 v[78:81], v[174:177], v[138:141], 0
	ds_read_b128 v[134:137], v216 offset:1024
	s_waitcnt lgkmcnt(6)
	v_mfma_f32_16x16x32_bf16 v[82:85], v[166:169], v[142:145], 0
	v_mfma_f32_16x16x32_bf16 v[86:89], v[174:177], v[142:145], 0
	ds_read_b128 v[138:141], v216 offset:3072
	s_waitcnt lgkmcnt(6)
	v_mfma_f32_16x16x32_bf16 v[90:93], v[166:169], v[146:149], 0
	v_mfma_f32_16x16x32_bf16 v[94:97], v[174:177], v[146:149], 0
	ds_read_b128 v[142:145], v216 offset:5120
	s_waitcnt lgkmcnt(6)
	v_mfma_f32_16x16x32_bf16 v[98:101], v[166:169], v[150:153], 0
	v_mfma_f32_16x16x32_bf16 v[102:105], v[174:177], v[150:153], 0
	ds_read_b128 v[146:149], v216 offset:7168
	s_waitcnt lgkmcnt(6)
	v_mfma_f32_16x16x32_bf16 v[106:109], v[166:169], v[154:157], 0
	v_mfma_f32_16x16x32_bf16 v[110:113], v[174:177], v[154:157], 0
	ds_read_b128 v[150:153], v216 offset:9216
	s_waitcnt lgkmcnt(6)
	v_mfma_f32_16x16x32_bf16 v[114:117], v[166:169], v[158:161], 0
	v_mfma_f32_16x16x32_bf16 v[118:121], v[174:177], v[158:161], 0
	ds_read_b128 v[154:157], v216 offset:11264
	s_waitcnt lgkmcnt(6)
	v_mfma_f32_16x16x32_bf16 v[122:125], v[166:169], v[162:165], 0
	v_mfma_f32_16x16x32_bf16 v[126:129], v[174:177], v[162:165], 0
	ds_read_b128 v[158:161], v216 offset:13312
	s_waitcnt lgkmcnt(6)
	v_mfma_f32_16x16x32_bf16 v[2:5], v[170:173], v[134:137], v[2:5]
	v_mfma_f32_16x16x32_bf16 v[6:9], v[178:181], v[134:137], v[6:9]
	ds_read_b128 v[162:165], v216 offset:15360
	s_waitcnt lgkmcnt(6)
	v_mfma_f32_16x16x32_bf16 v[10:13], v[170:173], v[138:141], v[10:13]
	v_mfma_f32_16x16x32_bf16 v[14:17], v[178:181], v[138:141], v[14:17]
	ds_read_b128 v[134:137], v216 offset:17408
	s_waitcnt lgkmcnt(6)
	v_mfma_f32_16x16x32_bf16 v[18:21], v[170:173], v[142:145], v[18:21]
	v_mfma_f32_16x16x32_bf16 v[22:25], v[178:181], v[142:145], v[22:25]
	ds_read_b128 v[138:141], v216 offset:19456
	s_waitcnt lgkmcnt(6)
	v_mfma_f32_16x16x32_bf16 v[26:29], v[170:173], v[146:149], v[26:29]
	v_mfma_f32_16x16x32_bf16 v[30:33], v[178:181], v[146:149], v[30:33]
	ds_read_b128 v[142:145], v216 offset:21504
	s_waitcnt lgkmcnt(6)
	v_mfma_f32_16x16x32_bf16 v[34:37], v[170:173], v[150:153], v[34:37]
	v_mfma_f32_16x16x32_bf16 v[38:41], v[178:181], v[150:153], v[38:41]
	ds_read_b128 v[146:149], v216 offset:23552
	s_waitcnt lgkmcnt(6)
	v_mfma_f32_16x16x32_bf16 v[42:45], v[170:173], v[154:157], v[42:45]
	v_mfma_f32_16x16x32_bf16 v[46:49], v[178:181], v[154:157], v[46:49]
	ds_read_b128 v[150:153], v216 offset:25600
	s_waitcnt lgkmcnt(6)
	v_mfma_f32_16x16x32_bf16 v[50:53], v[170:173], v[158:161], v[50:53]
	v_mfma_f32_16x16x32_bf16 v[54:57], v[178:181], v[158:161], v[54:57]
	ds_read_b128 v[154:157], v216 offset:27648
	s_waitcnt lgkmcnt(6)
	v_mfma_f32_16x16x32_bf16 v[58:61], v[170:173], v[162:165], v[58:61]
	v_mfma_f32_16x16x32_bf16 v[62:65], v[178:181], v[162:165], v[62:65]
	ds_read_b128 v[158:161], v216 offset:29696
	s_waitcnt lgkmcnt(6)
	v_mfma_f32_16x16x32_bf16 v[66:69], v[170:173], v[134:137], v[66:69]
	v_mfma_f32_16x16x32_bf16 v[70:73], v[178:181], v[134:137], v[70:73]
	ds_read_b128 v[162:165], v216 offset:31744
	s_waitcnt vmcnt(36) lgkmcnt(0)
	s_barrier
	v_mfma_f32_16x16x32_bf16 v[74:77], v[170:173], v[138:141], v[74:77]
	s_add_u32 m0, s22, 0x0
	v_mov_b32_e32 v223, v217
	global_load_lds_dwordx4 v223, s[6:7]
	v_mfma_f32_16x16x32_bf16 v[78:81], v[178:181], v[138:141], v[78:81]
	s_add_u32 m0, s22, 0x400
	v_add_u32_e32 v224, 0x40, v217
	global_load_lds_dwordx4 v224, s[6:7]
	ds_read_b128 v[134:137], v216 offset:32768
	s_waitcnt lgkmcnt(6)
	v_mfma_f32_16x16x32_bf16 v[82:85], v[170:173], v[142:145], v[82:85]
	s_add_u32 m0, s22, 0x800
	v_add_u32_e32 v223, 0x8000, v217
	global_load_lds_dwordx4 v223, s[6:7]
	v_mfma_f32_16x16x32_bf16 v[86:89], v[178:181], v[142:145], v[86:89]
	s_add_u32 m0, s22, 0xc00
	v_add_u32_e32 v224, 0x8040, v217
	global_load_lds_dwordx4 v224, s[6:7]
	ds_read_b128 v[138:141], v216 offset:34816
	s_waitcnt lgkmcnt(6)
	v_mfma_f32_16x16x32_bf16 v[90:93], v[170:173], v[146:149], v[90:93]
	s_add_u32 m0, s22, 0x1000
	v_add_u32_e32 v223, 0x10000, v217
	global_load_lds_dwordx4 v223, s[6:7]
	v_mfma_f32_16x16x32_bf16 v[94:97], v[178:181], v[146:149], v[94:97]
	s_add_u32 m0, s22, 0x1400
	v_add_u32_e32 v224, 0x10040, v217
	global_load_lds_dwordx4 v224, s[6:7]
	ds_read_b128 v[142:145], v216 offset:36864
	s_waitcnt lgkmcnt(6)
	v_mfma_f32_16x16x32_bf16 v[98:101], v[170:173], v[150:153], v[98:101]
	s_add_u32 m0, s22, 0x1800
	v_add_u32_e32 v223, 0x18000, v217
	global_load_lds_dwordx4 v223, s[6:7]
	v_mfma_f32_16x16x32_bf16 v[102:105], v[178:181], v[150:153], v[102:105]
	s_add_u32 m0, s22, 0x1c00
	v_add_u32_e32 v224, 0x18040, v217
	global_load_lds_dwordx4 v224, s[6:7]
	ds_read_b128 v[146:149], v216 offset:38912
	s_waitcnt lgkmcnt(6)
	v_mfma_f32_16x16x32_bf16 v[106:109], v[170:173], v[154:157], v[106:109]
	v_mfma_f32_16x16x32_bf16 v[110:113], v[178:181], v[154:157], v[110:113]
	ds_read_b128 v[150:153], v216 offset:40960
	s_waitcnt lgkmcnt(6)
	v_mfma_f32_16x16x32_bf16 v[114:117], v[170:173], v[158:161], v[114:117]
	v_mfma_f32_16x16x32_bf16 v[118:121], v[178:181], v[158:161], v[118:121]
	ds_read_b128 v[154:157], v216 offset:43008
	s_waitcnt lgkmcnt(6)
	v_mfma_f32_16x16x32_bf16 v[122:125], v[170:173], v[162:165], v[122:125]
	v_mfma_f32_16x16x32_bf16 v[126:129], v[178:181], v[162:165], v[126:129]
	v_add_u32_e32 v217, 0x80, v217
	v_add_u32_e32 v220, 0x800, v220
	v_add_u32_e32 v221, 0x800, v221
	ds_read_b128 v[158:161], v216 offset:45056
	s_waitcnt vmcnt(8) lgkmcnt(6)
	v_mfma_f32_16x16x32_bf16 v[2:5], v[196:199], v[134:137], v[2:5]
	global_load_dwordx4 v[166:169], v220, s[8:9]
	v_mfma_f32_16x16x32_bf16 v[6:9], v[204:207], v[134:137], v[6:9]
	global_load_dwordx4 v[170:173], v220, s[8:9] offset:1024
	ds_read_b128 v[162:165], v216 offset:47104
	s_waitcnt lgkmcnt(6)
	v_mfma_f32_16x16x32_bf16 v[10:13], v[196:199], v[138:141], v[10:13]
	global_load_dwordx4 v[174:177], v221, s[8:9]
	v_mfma_f32_16x16x32_bf16 v[14:17], v[204:207], v[138:141], v[14:17]
	global_load_dwordx4 v[178:181], v221, s[8:9] offset:1024
	ds_read_b128 v[134:137], v216 offset:49152
	s_waitcnt lgkmcnt(6)
	v_mfma_f32_16x16x32_bf16 v[18:21], v[196:199], v[142:145], v[18:21]
	v_mfma_f32_16x16x32_bf16 v[22:25], v[204:207], v[142:145], v[22:25]
	ds_read_b128 v[138:141], v216 offset:51200
	s_waitcnt lgkmcnt(6)
	v_mfma_f32_16x16x32_bf16 v[26:29], v[196:199], v[146:149], v[26:29]
	v_mfma_f32_16x16x32_bf16 v[30:33], v[204:207], v[146:149], v[30:33]
	ds_read_b128 v[142:145], v216 offset:53248
	s_waitcnt lgkmcnt(6)
	v_mfma_f32_16x16x32_bf16 v[34:37], v[196:199], v[150:153], v[34:37]
	v_mfma_f32_16x16x32_bf16 v[38:41], v[204:207], v[150:153], v[38:41]
	ds_read_b128 v[146:149], v216 offset:55296
	s_waitcnt lgkmcnt(6)
	v_mfma_f32_16x16x32_bf16 v[42:45], v[196:199], v[154:157], v[42:45]
	v_mfma_f32_16x16x32_bf16 v[46:49], v[204:207], v[154:157], v[46:49]
	ds_read_b128 v[150:153], v216 offset:57344
	s_waitcnt lgkmcnt(6)
	v_mfma_f32_16x16x32_bf16 v[50:53], v[196:199], v[158:161], v[50:53]
	v_mfma_f32_16x16x32_bf16 v[54:57], v[204:207], v[158:161], v[54:57]
	ds_read_b128 v[154:157], v216 offset:59392
	s_waitcnt lgkmcnt(6)
	v_mfma_f32_16x16x32_bf16 v[58:61], v[196:199], v[162:165], v[58:61]
	v_mfma_f32_16x16x32_bf16 v[62:65], v[204:207], v[162:165], v[62:65]
	ds_read_b128 v[158:161], v216 offset:61440
	s_waitcnt lgkmcnt(6)
	v_mfma_f32_16x16x32_bf16 v[66:69], v[196:199], v[134:137], v[66:69]
	v_mfma_f32_16x16x32_bf16 v[70:73], v[204:207], v[134:137], v[70:73]
	ds_read_b128 v[162:165], v216 offset:63488
	s_waitcnt lgkmcnt(6)
	v_mfma_f32_16x16x32_bf16 v[74:77], v[196:199], v[138:141], v[74:77]
	v_mfma_f32_16x16x32_bf16 v[78:81], v[204:207], v[138:141], v[78:81]
	ds_read_b128 v[134:137], v216 offset:33792
	s_waitcnt lgkmcnt(6)
	v_mfma_f32_16x16x32_bf16 v[82:85], v[196:199], v[142:145], v[82:85]
	v_mfma_f32_16x16x32_bf16 v[86:89], v[204:207], v[142:145], v[86:89]
	ds_read_b128 v[138:141], v216 offset:35840
	s_waitcnt lgkmcnt(6)
	v_mfma_f32_16x16x32_bf16 v[90:93], v[196:199], v[146:149], v[90:93]
	v_mfma_f32_16x16x32_bf16 v[94:97], v[204:207], v[146:149], v[94:97]
	ds_read_b128 v[142:145], v216 offset:37888
	s_waitcnt lgkmcnt(6)
	v_mfma_f32_16x16x32_bf16 v[98:101], v[196:199], v[150:153], v[98:101]
	v_mfma_f32_16x16x32_bf16 v[102:105], v[204:207], v[150:153], v[102:105]
	ds_read_b128 v[146:149], v216 offset:39936
	s_waitcnt lgkmcnt(6)
	v_mfma_f32_16x16x32_bf16 v[106:109], v[196:199], v[154:157], v[106:109]
	v_mfma_f32_16x16x32_bf16 v[110:113], v[204:207], v[154:157], v[110:113]
	ds_read_b128 v[150:153], v216 offset:41984
	s_waitcnt lgkmcnt(6)
	v_mfma_f32_16x16x32_bf16 v[114:117], v[196:199], v[158:161], v[114:117]
	v_mfma_f32_16x16x32_bf16 v[118:121], v[204:207], v[158:161], v[118:121]
	ds_read_b128 v[154:157], v216 offset:44032
	s_waitcnt lgkmcnt(6)
	v_mfma_f32_16x16x32_bf16 v[122:125], v[196:199], v[162:165], v[122:125]
	v_mfma_f32_16x16x32_bf16 v[126:129], v[204:207], v[162:165], v[126:129]
	ds_read_b128 v[158:161], v216 offset:46080
	s_waitcnt lgkmcnt(6)
	v_mfma_f32_16x16x32_bf16 v[2:5], v[200:203], v[134:137], v[2:5]
	v_mfma_f32_16x16x32_bf16 v[6:9], v[212:215], v[134:137], v[6:9]
	ds_read_b128 v[162:165], v216 offset:48128
	s_waitcnt lgkmcnt(6)
	v_mfma_f32_16x16x32_bf16 v[10:13], v[200:203], v[138:141], v[10:13]
	v_mfma_f32_16x16x32_bf16 v[14:17], v[212:215], v[138:141], v[14:17]
	ds_read_b128 v[134:137], v216 offset:50176
	s_waitcnt lgkmcnt(6)
	v_mfma_f32_16x16x32_bf16 v[18:21], v[200:203], v[142:145], v[18:21]
	v_mfma_f32_16x16x32_bf16 v[22:25], v[212:215], v[142:145], v[22:25]
	ds_read_b128 v[138:141], v216 offset:52224
	s_waitcnt lgkmcnt(6)
	v_mfma_f32_16x16x32_bf16 v[26:29], v[200:203], v[146:149], v[26:29]
	v_mfma_f32_16x16x32_bf16 v[30:33], v[212:215], v[146:149], v[30:33]
	ds_read_b128 v[142:145], v216 offset:54272
	s_waitcnt lgkmcnt(6)
	v_mfma_f32_16x16x32_bf16 v[34:37], v[200:203], v[150:153], v[34:37]
	v_mfma_f32_16x16x32_bf16 v[38:41], v[212:215], v[150:153], v[38:41]
	ds_read_b128 v[146:149], v216 offset:56320
	s_waitcnt lgkmcnt(6)
	v_mfma_f32_16x16x32_bf16 v[42:45], v[200:203], v[154:157], v[42:45]
	v_mfma_f32_16x16x32_bf16 v[46:49], v[212:215], v[154:157], v[46:49]
	ds_read_b128 v[150:153], v216 offset:58368
	s_waitcnt lgkmcnt(6)
	v_mfma_f32_16x16x32_bf16 v[50:53], v[200:203], v[158:161], v[50:53]
	v_mfma_f32_16x16x32_bf16 v[54:57], v[212:215], v[158:161], v[54:57]
	ds_read_b128 v[154:157], v216 offset:60416
	s_waitcnt lgkmcnt(6)
	v_mfma_f32_16x16x32_bf16 v[58:61], v[200:203], v[162:165], v[58:61]
	v_mfma_f32_16x16x32_bf16 v[62:65], v[212:215], v[162:165], v[62:65]
	ds_read_b128 v[158:161], v216 offset:62464
	s_waitcnt lgkmcnt(6)
	v_mfma_f32_16x16x32_bf16 v[66:69], v[200:203], v[134:137], v[66:69]
	v_mfma_f32_16x16x32_bf16 v[70:73], v[212:215], v[134:137], v[70:73]
	ds_read_b128 v[162:165], v216 offset:64512
	s_waitcnt vmcnt(4) lgkmcnt(0)
	s_barrier
	v_mfma_f32_16x16x32_bf16 v[74:77], v[200:203], v[138:141], v[74:77]
	s_add_u32 m0, s22, 0x8000
	v_mov_b32_e32 v223, v217
	global_load_lds_dwordx4 v223, s[6:7]
	v_mfma_f32_16x16x32_bf16 v[78:81], v[212:215], v[138:141], v[78:81]
	s_add_u32 m0, s22, 0x8400
	v_add_u32_e32 v224, 0x40, v217
	global_load_lds_dwordx4 v224, s[6:7]
	ds_read_b128 v[134:137], v216
	s_waitcnt lgkmcnt(6)
	v_mfma_f32_16x16x32_bf16 v[82:85], v[200:203], v[142:145], v[82:85]
	s_add_u32 m0, s22, 0x8800
	v_add_u32_e32 v223, 0x8000, v217
	global_load_lds_dwordx4 v223, s[6:7]
	v_mfma_f32_16x16x32_bf16 v[86:89], v[212:215], v[142:145], v[86:89]
	s_add_u32 m0, s22, 0x8c00
	v_add_u32_e32 v224, 0x8040, v217
	global_load_lds_dwordx4 v224, s[6:7]
	ds_read_b128 v[138:141], v216 offset:2048
	s_waitcnt lgkmcnt(6)
	v_mfma_f32_16x16x32_bf16 v[90:93], v[200:203], v[146:149], v[90:93]
	s_add_u32 m0, s22, 0x9000
	v_add_u32_e32 v223, 0x10000, v217
	global_load_lds_dwordx4 v223, s[6:7]
	v_mfma_f32_16x16x32_bf16 v[94:97], v[212:215], v[146:149], v[94:97]
	s_add_u32 m0, s22, 0x9400
	v_add_u32_e32 v224, 0x10040, v217
	global_load_lds_dwordx4 v224, s[6:7]
	ds_read_b128 v[142:145], v216 offset:4096
	s_waitcnt lgkmcnt(6)
	v_mfma_f32_16x16x32_bf16 v[98:101], v[200:203], v[150:153], v[98:101]
	s_add_u32 m0, s22, 0x9800
	v_add_u32_e32 v223, 0x18000, v217
	global_load_lds_dwordx4 v223, s[6:7]
	v_mfma_f32_16x16x32_bf16 v[102:105], v[212:215], v[150:153], v[102:105]
	s_add_u32 m0, s22, 0x9c00
	v_add_u32_e32 v224, 0x18040, v217
	global_load_lds_dwordx4 v224, s[6:7]
	ds_read_b128 v[146:149], v216 offset:6144
	s_waitcnt lgkmcnt(6)
	v_mfma_f32_16x16x32_bf16 v[106:109], v[200:203], v[154:157], v[106:109]
	v_mfma_f32_16x16x32_bf16 v[110:113], v[212:215], v[154:157], v[110:113]
	ds_read_b128 v[150:153], v216 offset:8192
	s_waitcnt lgkmcnt(6)
	v_mfma_f32_16x16x32_bf16 v[114:117], v[200:203], v[158:161], v[114:117]
	v_mfma_f32_16x16x32_bf16 v[118:121], v[212:215], v[158:161], v[118:121]
	ds_read_b128 v[154:157], v216 offset:10240
	s_waitcnt lgkmcnt(6)
	v_mfma_f32_16x16x32_bf16 v[122:125], v[200:203], v[162:165], v[122:125]
	v_mfma_f32_16x16x32_bf16 v[126:129], v[212:215], v[162:165], v[126:129]
	v_add_u32_e32 v217, 0x80, v217
	v_add_u32_e32 v220, 0x800, v220
	v_add_u32_e32 v221, 0x800, v221
	s_mov_b32 s16, 6
.Lg256b_w1_loop:
	ds_read_b128 v[158:161], v216 offset:12288
	s_waitcnt vmcnt(8) lgkmcnt(6)
	v_mfma_f32_16x16x32_bf16 v[2:5], v[166:169], v[134:137], v[2:5]
	global_load_dwordx4 v[196:199], v220, s[8:9]
	v_mfma_f32_16x16x32_bf16 v[6:9], v[174:177], v[134:137], v[6:9]
	global_load_dwordx4 v[200:203], v220, s[8:9] offset:1024
	ds_read_b128 v[162:165], v216 offset:14336
	s_waitcnt lgkmcnt(6)
	v_mfma_f32_16x16x32_bf16 v[10:13], v[166:169], v[138:141], v[10:13]
	global_load_dwordx4 v[204:207], v221, s[8:9]
	v_mfma_f32_16x16x32_bf16 v[14:17], v[174:177], v[138:141], v[14:17]
	global_load_dwordx4 v[212:215], v221, s[8:9] offset:1024
	ds_read_b128 v[134:137], v216 offset:16384
	s_waitcnt lgkmcnt(6)
	v_mfma_f32_16x16x32_bf16 v[18:21], v[166:169], v[142:145], v[18:21]
	v_mfma_f32_16x16x32_bf16 v[22:25], v[174:177], v[142:145], v[22:25]
	ds_read_b128 v[138:141], v216 offset:18432
	s_waitcnt lgkmcnt(6)
	v_mfma_f32_16x16x32_bf16 v[26:29], v[166:169], v[146:149], v[26:29]
	v_mfma_f32_16x16x32_bf16 v[30:33], v[174:177], v[146:149], v[30:33]
	ds_read_b128 v[142:145], v216 offset:20480
	s_waitcnt lgkmcnt(6)
	v_mfma_f32_16x16x32_bf16 v[34:37], v[166:169], v[150:153], v[34:37]
	v_mfma_f32_16x16x32_bf16 v[38:41], v[174:177], v[150:153], v[38:41]
	ds_read_b128 v[146:149], v216 offset:22528
	s_waitcnt lgkmcnt(6)
	v_mfma_f32_16x16x32_bf16 v[42:45], v[166:169], v[154:157], v[42:45]
	v_mfma_f32_16x16x32_bf16 v[46:49], v[174:177], v[154:157], v[46:49]
	ds_read_b128 v[150:153], v216 offset:24576
	s_waitcnt lgkmcnt(6)
	v_mfma_f32_16x16x32_bf16 v[50:53], v[166:169], v[158:161], v[50:53]
	v_mfma_f32_16x16x32_bf16 v[54:57], v[174:177], v[158:161], v[54:57]
	ds_read_b128 v[154:157], v216 offset:26624
	s_waitcnt lgkmcnt(6)
	v_mfma_f32_16x16x32_bf16 v[58:61], v[166:169], v[162:165], v[58:61]
	v_mfma_f32_16x16x32_bf16 v[62:65], v[174:177], v[162:165], v[62:65]
	ds_read_b128 v[158:161], v216 offset:28672
	s_waitcnt lgkmcnt(6)
	v_mfma_f32_16x16x32_bf16 v[66:69], v[166:169], v[134:137], v[66:69]
	v_mfma_f32_16x16x32_bf16 v[70:73], v[174:177], v[134:137], v[70:73]
	ds_read_b128 v[162:165], v216 offset:30720
	s_waitcnt lgkmcnt(6)
	v_mfma_f32_16x16x32_bf16 v[74:77], v[166:169], v[138:141], v[74:77]
	v_mfma_f32_16x16x32_bf16 v[78:81], v[174:177], v[138:141], v[78:81]
	ds_read_b128 v[134:137], v216 offset:1024
	s_waitcnt lgkmcnt(6)
	v_mfma_f32_16x16x32_bf16 v[82:85], v[166:169], v[142:145], v[82:85]
	v_mfma_f32_16x16x32_bf16 v[86:89], v[174:177], v[142:145], v[86:89]
	ds_read_b128 v[138:141], v216 offset:3072
	s_waitcnt lgkmcnt(6)
	v_mfma_f32_16x16x32_bf16 v[90:93], v[166:169], v[146:149], v[90:93]
	v_mfma_f32_16x16x32_bf16 v[94:97], v[174:177], v[146:149], v[94:97]
	ds_read_b128 v[142:145], v216 offset:5120
	s_waitcnt lgkmcnt(6)
	v_mfma_f32_16x16x32_bf16 v[98:101], v[166:169], v[150:153], v[98:101]
	v_mfma_f32_16x16x32_bf16 v[102:105], v[174:177], v[150:153], v[102:105]
	ds_read_b128 v[146:149], v216 offset:7168
	s_waitcnt lgkmcnt(6)
	v_mfma_f32_16x16x32_bf16 v[106:109], v[166:169], v[154:157], v[106:109]
	v_mfma_f32_16x16x32_bf16 v[110:113], v[174:177], v[154:157], v[110:113]
	ds_read_b128 v[150:153], v216 offset:9216
	s_waitcnt lgkmcnt(6)
	v_mfma_f32_16x16x32_bf16 v[114:117], v[166:169], v[158:161], v[114:117]
	v_mfma_f32_16x16x32_bf16 v[118:121], v[174:177], v[158:161], v[118:121]
	ds_read_b128 v[154:157], v216 offset:11264
	s_waitcnt lgkmcnt(6)
	v_mfma_f32_16x16x32_bf16 v[122:125], v[166:169], v[162:165], v[122:125]
	v_mfma_f32_16x16x32_bf16 v[126:129], v[174:177], v[162:165], v[126:129]
	ds_read_b128 v[158:161], v216 offset:13312
	s_waitcnt lgkmcnt(6)
	v_mfma_f32_16x16x32_bf16 v[2:5], v[170:173], v[134:137], v[2:5]
	v_mfma_f32_16x16x32_bf16 v[6:9], v[178:181], v[134:137], v[6:9]
	ds_read_b128 v[162:165], v216 offset:15360
	s_waitcnt lgkmcnt(6)
	v_mfma_f32_16x16x32_bf16 v[10:13], v[170:173], v[138:141], v[10:13]
	v_mfma_f32_16x16x32_bf16 v[14:17], v[178:181], v[138:141], v[14:17]
	ds_read_b128 v[134:137], v216 offset:17408
	s_waitcnt lgkmcnt(6)
	v_mfma_f32_16x16x32_bf16 v[18:21], v[170:173], v[142:145], v[18:21]
	v_mfma_f32_16x16x32_bf16 v[22:25], v[178:181], v[142:145], v[22:25]
	ds_read_b128 v[138:141], v216 offset:19456
	s_waitcnt lgkmcnt(6)
	v_mfma_f32_16x16x32_bf16 v[26:29], v[170:173], v[146:149], v[26:29]
	v_mfma_f32_16x16x32_bf16 v[30:33], v[178:181], v[146:149], v[30:33]
	ds_read_b128 v[142:145], v216 offset:21504
	s_waitcnt lgkmcnt(6)
	v_mfma_f32_16x16x32_bf16 v[34:37], v[170:173], v[150:153], v[34:37]
	v_mfma_f32_16x16x32_bf16 v[38:41], v[178:181], v[150:153], v[38:41]
	ds_read_b128 v[146:149], v216 offset:23552
	s_waitcnt lgkmcnt(6)
	v_mfma_f32_16x16x32_bf16 v[42:45], v[170:173], v[154:157], v[42:45]
	v_mfma_f32_16x16x32_bf16 v[46:49], v[178:181], v[154:157], v[46:49]
	ds_read_b128 v[150:153], v216 offset:25600
	s_waitcnt lgkmcnt(6)
	v_mfma_f32_16x16x32_bf16 v[50:53], v[170:173], v[158:161], v[50:53]
	v_mfma_f32_16x16x32_bf16 v[54:57], v[178:181], v[158:161], v[54:57]
	ds_read_b128 v[154:157], v216 offset:27648
	s_waitcnt lgkmcnt(6)
	v_mfma_f32_16x16x32_bf16 v[58:61], v[170:173], v[162:165], v[58:61]
	v_mfma_f32_16x16x32_bf16 v[62:65], v[178:181], v[162:165], v[62:65]
	ds_read_b128 v[158:161], v216 offset:29696
	s_waitcnt lgkmcnt(6)
	v_mfma_f32_16x16x32_bf16 v[66:69], v[170:173], v[134:137], v[66:69]
	v_mfma_f32_16x16x32_bf16 v[70:73], v[178:181], v[134:137], v[70:73]
	ds_read_b128 v[162:165], v216 offset:31744
	s_waitcnt vmcnt(4) lgkmcnt(0)
	s_barrier
	v_mfma_f32_16x16x32_bf16 v[74:77], v[170:173], v[138:141], v[74:77]
	s_add_u32 m0, s22, 0x0
	v_mov_b32_e32 v223, v217
	global_load_lds_dwordx4 v223, s[6:7]
	v_mfma_f32_16x16x32_bf16 v[78:81], v[178:181], v[138:141], v[78:81]
	s_add_u32 m0, s22, 0x400
	v_add_u32_e32 v224, 0x40, v217
	global_load_lds_dwordx4 v224, s[6:7]
	ds_read_b128 v[134:137], v216 offset:32768
	s_waitcnt lgkmcnt(6)
	v_mfma_f32_16x16x32_bf16 v[82:85], v[170:173], v[142:145], v[82:85]
	s_add_u32 m0, s22, 0x800
	v_add_u32_e32 v223, 0x8000, v217
	global_load_lds_dwordx4 v223, s[6:7]
	v_mfma_f32_16x16x32_bf16 v[86:89], v[178:181], v[142:145], v[86:89]
	s_add_u32 m0, s22, 0xc00
	v_add_u32_e32 v224, 0x8040, v217
	global_load_lds_dwordx4 v224, s[6:7]
	ds_read_b128 v[138:141], v216 offset:34816
	s_waitcnt lgkmcnt(6)
	v_mfma_f32_16x16x32_bf16 v[90:93], v[170:173], v[146:149], v[90:93]
	s_add_u32 m0, s22, 0x1000
	v_add_u32_e32 v223, 0x10000, v217
	global_load_lds_dwordx4 v223, s[6:7]
	v_mfma_f32_16x16x32_bf16 v[94:97], v[178:181], v[146:149], v[94:97]
	s_add_u32 m0, s22, 0x1400
	v_add_u32_e32 v224, 0x10040, v217
	global_load_lds_dwordx4 v224, s[6:7]
	ds_read_b128 v[142:145], v216 offset:36864
	s_waitcnt lgkmcnt(6)
	v_mfma_f32_16x16x32_bf16 v[98:101], v[170:173], v[150:153], v[98:101]
	s_add_u32 m0, s22, 0x1800
	v_add_u32_e32 v223, 0x18000, v217
	global_load_lds_dwordx4 v223, s[6:7]
	v_mfma_f32_16x16x32_bf16 v[102:105], v[178:181], v[150:153], v[102:105]
	s_add_u32 m0, s22, 0x1c00
	v_add_u32_e32 v224, 0x18040, v217
	global_load_lds_dwordx4 v224, s[6:7]
	ds_read_b128 v[146:149], v216 offset:38912
	s_waitcnt lgkmcnt(6)
	v_mfma_f32_16x16x32_bf16 v[106:109], v[170:173], v[154:157], v[106:109]
	v_mfma_f32_16x16x32_bf16 v[110:113], v[178:181], v[154:157], v[110:113]
	ds_read_b128 v[150:153], v216 offset:40960
	s_waitcnt lgkmcnt(6)
	v_mfma_f32_16x16x32_bf16 v[114:117], v[170:173], v[158:161], v[114:117]
	v_mfma_f32_16x16x32_bf16 v[118:121], v[178:181], v[158:161], v[118:121]
	ds_read_b128 v[154:157], v216 offset:43008
	s_waitcnt lgkmcnt(6)
	v_mfma_f32_16x16x32_bf16 v[122:125], v[170:173], v[162:165], v[122:125]
	v_mfma_f32_16x16x32_bf16 v[126:129], v[178:181], v[162:165], v[126:129]
	v_add_u32_e32 v217, 0x80, v217
	v_add_u32_e32 v220, 0x800, v220
	v_add_u32_e32 v221, 0x800, v221
	ds_read_b128 v[158:161], v216 offset:45056
	s_waitcnt vmcnt(8) lgkmcnt(6)
	v_mfma_f32_16x16x32_bf16 v[2:5], v[196:199], v[134:137], v[2:5]
	global_load_dwordx4 v[166:169], v220, s[8:9]
	v_mfma_f32_16x16x32_bf16 v[6:9], v[204:207], v[134:137], v[6:9]
	global_load_dwordx4 v[170:173], v220, s[8:9] offset:1024
	ds_read_b128 v[162:165], v216 offset:47104
	s_waitcnt lgkmcnt(6)
	v_mfma_f32_16x16x32_bf16 v[10:13], v[196:199], v[138:141], v[10:13]
	global_load_dwordx4 v[174:177], v221, s[8:9]
	v_mfma_f32_16x16x32_bf16 v[14:17], v[204:207], v[138:141], v[14:17]
	global_load_dwordx4 v[178:181], v221, s[8:9] offset:1024
	ds_read_b128 v[134:137], v216 offset:49152
	s_waitcnt lgkmcnt(6)
	v_mfma_f32_16x16x32_bf16 v[18:21], v[196:199], v[142:145], v[18:21]
	v_mfma_f32_16x16x32_bf16 v[22:25], v[204:207], v[142:145], v[22:25]
	ds_read_b128 v[138:141], v216 offset:51200
	s_waitcnt lgkmcnt(6)
	v_mfma_f32_16x16x32_bf16 v[26:29], v[196:199], v[146:149], v[26:29]
	v_mfma_f32_16x16x32_bf16 v[30:33], v[204:207], v[146:149], v[30:33]
	ds_read_b128 v[142:145], v216 offset:53248
	s_waitcnt lgkmcnt(6)
	v_mfma_f32_16x16x32_bf16 v[34:37], v[196:199], v[150:153], v[34:37]
	v_mfma_f32_16x16x32_bf16 v[38:41], v[204:207], v[150:153], v[38:41]
	ds_read_b128 v[146:149], v216 offset:55296
	s_waitcnt lgkmcnt(6)
	v_mfma_f32_16x16x32_bf16 v[42:45], v[196:199], v[154:157], v[42:45]
	v_mfma_f32_16x16x32_bf16 v[46:49], v[204:207], v[154:157], v[46:49]
	ds_read_b128 v[150:153], v216 offset:57344
	s_waitcnt lgkmcnt(6)
	v_mfma_f32_16x16x32_bf16 v[50:53], v[196:199], v[158:161], v[50:53]
	v_mfma_f32_16x16x32_bf16 v[54:57], v[204:207], v[158:161], v[54:57]
	ds_read_b128 v[154:157], v216 offset:59392
	s_waitcnt lgkmcnt(6)
	v_mfma_f32_16x16x32_bf16 v[58:61], v[196:199], v[162:165], v[58:61]
	v_mfma_f32_16x16x32_bf16 v[62:65], v[204:207], v[162:165], v[62:65]
	ds_read_b128 v[158:161], v216 offset:61440
	s_waitcnt lgkmcnt(6)
	v_mfma_f32_16x16x32_bf16 v[66:69], v[196:199], v[134:137], v[66:69]
	v_mfma_f32_16x16x32_bf16 v[70:73], v[204:207], v[134:137], v[70:73]
	ds_read_b128 v[162:165], v216 offset:63488
	s_waitcnt lgkmcnt(6)
	v_mfma_f32_16x16x32_bf16 v[74:77], v[196:199], v[138:141], v[74:77]
	v_mfma_f32_16x16x32_bf16 v[78:81], v[204:207], v[138:141], v[78:81]
	ds_read_b128 v[134:137], v216 offset:33792
	s_waitcnt lgkmcnt(6)
	v_mfma_f32_16x16x32_bf16 v[82:85], v[196:199], v[142:145], v[82:85]
	v_mfma_f32_16x16x32_bf16 v[86:89], v[204:207], v[142:145], v[86:89]
	ds_read_b128 v[138:141], v216 offset:35840
	s_waitcnt lgkmcnt(6)
	v_mfma_f32_16x16x32_bf16 v[90:93], v[196:199], v[146:149], v[90:93]
	v_mfma_f32_16x16x32_bf16 v[94:97], v[204:207], v[146:149], v[94:97]
	ds_read_b128 v[142:145], v216 offset:37888
	s_waitcnt lgkmcnt(6)
	v_mfma_f32_16x16x32_bf16 v[98:101], v[196:199], v[150:153], v[98:101]
	v_mfma_f32_16x16x32_bf16 v[102:105], v[204:207], v[150:153], v[102:105]
	ds_read_b128 v[146:149], v216 offset:39936
	s_waitcnt lgkmcnt(6)
	v_mfma_f32_16x16x32_bf16 v[106:109], v[196:199], v[154:157], v[106:109]
	v_mfma_f32_16x16x32_bf16 v[110:113], v[204:207], v[154:157], v[110:113]
	ds_read_b128 v[150:153], v216 offset:41984
	s_waitcnt lgkmcnt(6)
	v_mfma_f32_16x16x32_bf16 v[114:117], v[196:199], v[158:161], v[114:117]
	v_mfma_f32_16x16x32_bf16 v[118:121], v[204:207], v[158:161], v[118:121]
	ds_read_b128 v[154:157], v216 offset:44032
	s_waitcnt lgkmcnt(6)
	v_mfma_f32_16x16x32_bf16 v[122:125], v[196:199], v[162:165], v[122:125]
	v_mfma_f32_16x16x32_bf16 v[126:129], v[204:207], v[162:165], v[126:129]
	ds_read_b128 v[158:161], v216 offset:46080
	s_waitcnt lgkmcnt(6)
	v_mfma_f32_16x16x32_bf16 v[2:5], v[200:203], v[134:137], v[2:5]
	v_mfma_f32_16x16x32_bf16 v[6:9], v[212:215], v[134:137], v[6:9]
	ds_read_b128 v[162:165], v216 offset:48128
	s_waitcnt lgkmcnt(6)
	v_mfma_f32_16x16x32_bf16 v[10:13], v[200:203], v[138:141], v[10:13]
	v_mfma_f32_16x16x32_bf16 v[14:17], v[212:215], v[138:141], v[14:17]
	ds_read_b128 v[134:137], v216 offset:50176
	s_waitcnt lgkmcnt(6)
	v_mfma_f32_16x16x32_bf16 v[18:21], v[200:203], v[142:145], v[18:21]
	v_mfma_f32_16x16x32_bf16 v[22:25], v[212:215], v[142:145], v[22:25]
	ds_read_b128 v[138:141], v216 offset:52224
	s_waitcnt lgkmcnt(6)
	v_mfma_f32_16x16x32_bf16 v[26:29], v[200:203], v[146:149], v[26:29]
	v_mfma_f32_16x16x32_bf16 v[30:33], v[212:215], v[146:149], v[30:33]
	ds_read_b128 v[142:145], v216 offset:54272
	s_waitcnt lgkmcnt(6)
	v_mfma_f32_16x16x32_bf16 v[34:37], v[200:203], v[150:153], v[34:37]
	v_mfma_f32_16x16x32_bf16 v[38:41], v[212:215], v[150:153], v[38:41]
	ds_read_b128 v[146:149], v216 offset:56320
	s_waitcnt lgkmcnt(6)
	v_mfma_f32_16x16x32_bf16 v[42:45], v[200:203], v[154:157], v[42:45]
	v_mfma_f32_16x16x32_bf16 v[46:49], v[212:215], v[154:157], v[46:49]
	ds_read_b128 v[150:153], v216 offset:58368
	s_waitcnt lgkmcnt(6)
	v_mfma_f32_16x16x32_bf16 v[50:53], v[200:203], v[158:161], v[50:53]
	v_mfma_f32_16x16x32_bf16 v[54:57], v[212:215], v[158:161], v[54:57]
	ds_read_b128 v[154:157], v216 offset:60416
	s_waitcnt lgkmcnt(6)
	v_mfma_f32_16x16x32_bf16 v[58:61], v[200:203], v[162:165], v[58:61]
	v_mfma_f32_16x16x32_bf16 v[62:65], v[212:215], v[162:165], v[62:65]
	ds_read_b128 v[158:161], v216 offset:62464
	s_waitcnt lgkmcnt(6)
	v_mfma_f32_16x16x32_bf16 v[66:69], v[200:203], v[134:137], v[66:69]
	v_mfma_f32_16x16x32_bf16 v[70:73], v[212:215], v[134:137], v[70:73]
	ds_read_b128 v[162:165], v216 offset:64512
	s_waitcnt vmcnt(4) lgkmcnt(0)
	s_barrier
	v_mfma_f32_16x16x32_bf16 v[74:77], v[200:203], v[138:141], v[74:77]
	s_add_u32 m0, s22, 0x8000
	v_mov_b32_e32 v223, v217
	global_load_lds_dwordx4 v223, s[6:7]
	v_mfma_f32_16x16x32_bf16 v[78:81], v[212:215], v[138:141], v[78:81]
	s_add_u32 m0, s22, 0x8400
	v_add_u32_e32 v224, 0x40, v217
	global_load_lds_dwordx4 v224, s[6:7]
	ds_read_b128 v[134:137], v216
	s_waitcnt lgkmcnt(6)
	v_mfma_f32_16x16x32_bf16 v[82:85], v[200:203], v[142:145], v[82:85]
	s_add_u32 m0, s22, 0x8800
	v_add_u32_e32 v223, 0x8000, v217
	global_load_lds_dwordx4 v223, s[6:7]
	v_mfma_f32_16x16x32_bf16 v[86:89], v[212:215], v[142:145], v[86:89]
	s_add_u32 m0, s22, 0x8c00
	v_add_u32_e32 v224, 0x8040, v217
	global_load_lds_dwordx4 v224, s[6:7]
	ds_read_b128 v[138:141], v216 offset:2048
	s_waitcnt lgkmcnt(6)
	v_mfma_f32_16x16x32_bf16 v[90:93], v[200:203], v[146:149], v[90:93]
	s_add_u32 m0, s22, 0x9000
	v_add_u32_e32 v223, 0x10000, v217
	global_load_lds_dwordx4 v223, s[6:7]
	v_mfma_f32_16x16x32_bf16 v[94:97], v[212:215], v[146:149], v[94:97]
	s_add_u32 m0, s22, 0x9400
	v_add_u32_e32 v224, 0x10040, v217
	global_load_lds_dwordx4 v224, s[6:7]
	ds_read_b128 v[142:145], v216 offset:4096
	s_waitcnt lgkmcnt(6)
	v_mfma_f32_16x16x32_bf16 v[98:101], v[200:203], v[150:153], v[98:101]
	s_add_u32 m0, s22, 0x9800
	v_add_u32_e32 v223, 0x18000, v217
	global_load_lds_dwordx4 v223, s[6:7]
	v_mfma_f32_16x16x32_bf16 v[102:105], v[212:215], v[150:153], v[102:105]
	s_add_u32 m0, s22, 0x9c00
	v_add_u32_e32 v224, 0x18040, v217
	global_load_lds_dwordx4 v224, s[6:7]
	ds_read_b128 v[146:149], v216 offset:6144
	s_waitcnt lgkmcnt(6)
	v_mfma_f32_16x16x32_bf16 v[106:109], v[200:203], v[154:157], v[106:109]
	v_mfma_f32_16x16x32_bf16 v[110:113], v[212:215], v[154:157], v[110:113]
	ds_read_b128 v[150:153], v216 offset:8192
	s_waitcnt lgkmcnt(6)
	v_mfma_f32_16x16x32_bf16 v[114:117], v[200:203], v[158:161], v[114:117]
	v_mfma_f32_16x16x32_bf16 v[118:121], v[212:215], v[158:161], v[118:121]
	ds_read_b128 v[154:157], v216 offset:10240
	s_waitcnt lgkmcnt(6)
	v_mfma_f32_16x16x32_bf16 v[122:125], v[200:203], v[162:165], v[122:125]
	v_mfma_f32_16x16x32_bf16 v[126:129], v[212:215], v[162:165], v[126:129]
	v_add_u32_e32 v217, 0x80, v217
	v_add_u32_e32 v220, 0x800, v220
	v_add_u32_e32 v221, 0x800, v221
	s_sub_u32 s16, s16, 1
	s_cmp_lg_u32 s16, 0
	s_cbranch_scc1 .Lg256b_w1_loop
	s_add_u32 s12, s12, s83
	s_cmp_ge_u32 s12, 256
	s_cbranch_scc1 .Lg256b_w1_nonext
	s_lshr_b32 s3, s12, 6
	s_lshl_b32 s3, s3, 3
	s_add_u32 s3, s3, s65
	s_lshr_b32 s17, s3, 2
	s_and_b32 s3, s3, 3
	s_lshl_b32 s17, s17, 3
	s_bfe_u32 s23, s12, 0x30003
	s_add_u32 s13, s17, s23
	s_lshl_b32 s3, s3, 3
	s_and_b32 s23, s12, 7
	s_add_u32 s14, s3, s23
	s_lshl_b32 s13, s13, 8
	s_lshl_b32 s14, s14, 7
	s_lshl_b32 s3, s15, 6
	s_add_u32 s17, s3, s13
	s_mul_i32 s17, s17, 0x800
	s_add_u32 s6, s18, s17
	s_addc_u32 s7, s19, 0
	v_mov_b32_e32 v217, v218
	ds_read_b128 v[158:161], v216 offset:12288
	s_waitcnt vmcnt(8) lgkmcnt(6)
	v_mfma_f32_16x16x32_bf16 v[2:5], v[166:169], v[134:137], v[2:5]
	global_load_dwordx4 v[196:199], v220, s[8:9]
	v_mfma_f32_16x16x32_bf16 v[6:9], v[174:177], v[134:137], v[6:9]
	global_load_dwordx4 v[200:203], v220, s[8:9] offset:1024
	ds_read_b128 v[162:165], v216 offset:14336
	s_waitcnt lgkmcnt(6)
	v_mfma_f32_16x16x32_bf16 v[10:13], v[166:169], v[138:141], v[10:13]
	global_load_dwordx4 v[204:207], v221, s[8:9]
	v_mfma_f32_16x16x32_bf16 v[14:17], v[174:177], v[138:141], v[14:17]
	global_load_dwordx4 v[212:215], v221, s[8:9] offset:1024
	ds_read_b128 v[134:137], v216 offset:16384
	s_waitcnt lgkmcnt(6)
	v_mfma_f32_16x16x32_bf16 v[18:21], v[166:169], v[142:145], v[18:21]
	v_mfma_f32_16x16x32_bf16 v[22:25], v[174:177], v[142:145], v[22:25]
	ds_read_b128 v[138:141], v216 offset:18432
	s_waitcnt lgkmcnt(6)
	v_mfma_f32_16x16x32_bf16 v[26:29], v[166:169], v[146:149], v[26:29]
	v_mfma_f32_16x16x32_bf16 v[30:33], v[174:177], v[146:149], v[30:33]
	ds_read_b128 v[142:145], v216 offset:20480
	s_waitcnt lgkmcnt(6)
	v_mfma_f32_16x16x32_bf16 v[34:37], v[166:169], v[150:153], v[34:37]
	v_mfma_f32_16x16x32_bf16 v[38:41], v[174:177], v[150:153], v[38:41]
	ds_read_b128 v[146:149], v216 offset:22528
	s_waitcnt lgkmcnt(6)
	v_mfma_f32_16x16x32_bf16 v[42:45], v[166:169], v[154:157], v[42:45]
	v_mfma_f32_16x16x32_bf16 v[46:49], v[174:177], v[154:157], v[46:49]
	ds_read_b128 v[150:153], v216 offset:24576
	s_waitcnt lgkmcnt(6)
	v_mfma_f32_16x16x32_bf16 v[50:53], v[166:169], v[158:161], v[50:53]
	v_mfma_f32_16x16x32_bf16 v[54:57], v[174:177], v[158:161], v[54:57]
	ds_read_b128 v[154:157], v216 offset:26624
	s_waitcnt lgkmcnt(6)
	v_mfma_f32_16x16x32_bf16 v[58:61], v[166:169], v[162:165], v[58:61]
	v_mfma_f32_16x16x32_bf16 v[62:65], v[174:177], v[162:165], v[62:65]
	ds_read_b128 v[158:161], v216 offset:28672
	s_waitcnt lgkmcnt(6)
	v_mfma_f32_16x16x32_bf16 v[66:69], v[166:169], v[134:137], v[66:69]
	v_mfma_f32_16x16x32_bf16 v[70:73], v[174:177], v[134:137], v[70:73]
	ds_read_b128 v[162:165], v216 offset:30720
	s_waitcnt lgkmcnt(6)
	v_mfma_f32_16x16x32_bf16 v[74:77], v[166:169], v[138:141], v[74:77]
	v_mfma_f32_16x16x32_bf16 v[78:81], v[174:177], v[138:141], v[78:81]
	ds_read_b128 v[134:137], v216 offset:1024
	s_waitcnt lgkmcnt(6)
	v_mfma_f32_16x16x32_bf16 v[82:85], v[166:169], v[142:145], v[82:85]
	v_mfma_f32_16x16x32_bf16 v[86:89], v[174:177], v[142:145], v[86:89]
	ds_read_b128 v[138:141], v216 offset:3072
	s_waitcnt lgkmcnt(6)
	v_mfma_f32_16x16x32_bf16 v[90:93], v[166:169], v[146:149], v[90:93]
	v_mfma_f32_16x16x32_bf16 v[94:97], v[174:177], v[146:149], v[94:97]
	ds_read_b128 v[142:145], v216 offset:5120
	s_waitcnt lgkmcnt(6)
	v_mfma_f32_16x16x32_bf16 v[98:101], v[166:169], v[150:153], v[98:101]
	v_mfma_f32_16x16x32_bf16 v[102:105], v[174:177], v[150:153], v[102:105]
	ds_read_b128 v[146:149], v216 offset:7168
	s_waitcnt lgkmcnt(6)
	v_mfma_f32_16x16x32_bf16 v[106:109], v[166:169], v[154:157], v[106:109]
	v_mfma_f32_16x16x32_bf16 v[110:113], v[174:177], v[154:157], v[110:113]
	ds_read_b128 v[150:153], v216 offset:9216
	s_waitcnt lgkmcnt(6)
	v_mfma_f32_16x16x32_bf16 v[114:117], v[166:169], v[158:161], v[114:117]
	v_mfma_f32_16x16x32_bf16 v[118:121], v[174:177], v[158:161], v[118:121]
	ds_read_b128 v[154:157], v216 offset:11264
	s_waitcnt lgkmcnt(6)
	v_mfma_f32_16x16x32_bf16 v[122:125], v[166:169], v[162:165], v[122:125]
	v_mfma_f32_16x16x32_bf16 v[126:129], v[174:177], v[162:165], v[126:129]
	ds_read_b128 v[158:161], v216 offset:13312
	s_waitcnt lgkmcnt(6)
	v_mfma_f32_16x16x32_bf16 v[2:5], v[170:173], v[134:137], v[2:5]
	v_mfma_f32_16x16x32_bf16 v[6:9], v[178:181], v[134:137], v[6:9]
	ds_read_b128 v[162:165], v216 offset:15360
	s_waitcnt lgkmcnt(6)
	v_mfma_f32_16x16x32_bf16 v[10:13], v[170:173], v[138:141], v[10:13]
	v_mfma_f32_16x16x32_bf16 v[14:17], v[178:181], v[138:141], v[14:17]
	ds_read_b128 v[134:137], v216 offset:17408
	s_waitcnt lgkmcnt(6)
	v_mfma_f32_16x16x32_bf16 v[18:21], v[170:173], v[142:145], v[18:21]
	v_mfma_f32_16x16x32_bf16 v[22:25], v[178:181], v[142:145], v[22:25]
	ds_read_b128 v[138:141], v216 offset:19456
	s_waitcnt lgkmcnt(6)
	v_mfma_f32_16x16x32_bf16 v[26:29], v[170:173], v[146:149], v[26:29]
	v_mfma_f32_16x16x32_bf16 v[30:33], v[178:181], v[146:149], v[30:33]
	ds_read_b128 v[142:145], v216 offset:21504
	s_waitcnt lgkmcnt(6)
	v_mfma_f32_16x16x32_bf16 v[34:37], v[170:173], v[150:153], v[34:37]
	v_mfma_f32_16x16x32_bf16 v[38:41], v[178:181], v[150:153], v[38:41]
	ds_read_b128 v[146:149], v216 offset:23552
	s_waitcnt lgkmcnt(6)
	v_mfma_f32_16x16x32_bf16 v[42:45], v[170:173], v[154:157], v[42:45]
	v_mfma_f32_16x16x32_bf16 v[46:49], v[178:181], v[154:157], v[46:49]
	ds_read_b128 v[150:153], v216 offset:25600
	s_waitcnt lgkmcnt(6)
	v_mfma_f32_16x16x32_bf16 v[50:53], v[170:173], v[158:161], v[50:53]
	v_mfma_f32_16x16x32_bf16 v[54:57], v[178:181], v[158:161], v[54:57]
	ds_read_b128 v[154:157], v216 offset:27648
	s_waitcnt lgkmcnt(6)
	v_mfma_f32_16x16x32_bf16 v[58:61], v[170:173], v[162:165], v[58:61]
	v_mfma_f32_16x16x32_bf16 v[62:65], v[178:181], v[162:165], v[62:65]
	ds_read_b128 v[158:161], v216 offset:29696
	s_waitcnt lgkmcnt(6)
	v_mfma_f32_16x16x32_bf16 v[66:69], v[170:173], v[134:137], v[66:69]
	v_mfma_f32_16x16x32_bf16 v[70:73], v[178:181], v[134:137], v[70:73]
	ds_read_b128 v[162:165], v216 offset:31744
	s_waitcnt vmcnt(4) lgkmcnt(0)
	s_barrier
	v_mfma_f32_16x16x32_bf16 v[74:77], v[170:173], v[138:141], v[74:77]
	s_add_u32 m0, s22, 0x0
	v_mov_b32_e32 v223, v217
	global_load_lds_dwordx4 v223, s[6:7]
	v_mfma_f32_16x16x32_bf16 v[78:81], v[178:181], v[138:141], v[78:81]
	s_add_u32 m0, s22, 0x400
	v_add_u32_e32 v224, 0x40, v217
	global_load_lds_dwordx4 v224, s[6:7]
	ds_read_b128 v[134:137], v216 offset:32768
	s_waitcnt lgkmcnt(6)
	v_mfma_f32_16x16x32_bf16 v[82:85], v[170:173], v[142:145], v[82:85]
	s_add_u32 m0, s22, 0x800
	v_add_u32_e32 v223, 0x8000, v217
	global_load_lds_dwordx4 v223, s[6:7]
	v_mfma_f32_16x16x32_bf16 v[86:89], v[178:181], v[142:145], v[86:89]
	s_add_u32 m0, s22, 0xc00
	v_add_u32_e32 v224, 0x8040, v217
	global_load_lds_dwordx4 v224, s[6:7]
	ds_read_b128 v[138:141], v216 offset:34816
	s_waitcnt lgkmcnt(6)
	v_mfma_f32_16x16x32_bf16 v[90:93], v[170:173], v[146:149], v[90:93]
	s_add_u32 m0, s22, 0x1000
	v_add_u32_e32 v223, 0x10000, v217
	global_load_lds_dwordx4 v223, s[6:7]
	v_mfma_f32_16x16x32_bf16 v[94:97], v[178:181], v[146:149], v[94:97]
	s_add_u32 m0, s22, 0x1400
	v_add_u32_e32 v224, 0x10040, v217
	global_load_lds_dwordx4 v224, s[6:7]
	ds_read_b128 v[142:145], v216 offset:36864
	s_waitcnt lgkmcnt(6)
	v_mfma_f32_16x16x32_bf16 v[98:101], v[170:173], v[150:153], v[98:101]
	s_add_u32 m0, s22, 0x1800
	v_add_u32_e32 v223, 0x18000, v217
	global_load_lds_dwordx4 v223, s[6:7]
	v_mfma_f32_16x16x32_bf16 v[102:105], v[178:181], v[150:153], v[102:105]
	s_add_u32 m0, s22, 0x1c00
	v_add_u32_e32 v224, 0x18040, v217
	global_load_lds_dwordx4 v224, s[6:7]
	ds_read_b128 v[146:149], v216 offset:38912
	s_waitcnt lgkmcnt(6)
	v_mfma_f32_16x16x32_bf16 v[106:109], v[170:173], v[154:157], v[106:109]
	v_mfma_f32_16x16x32_bf16 v[110:113], v[178:181], v[154:157], v[110:113]
	ds_read_b128 v[150:153], v216 offset:40960
	s_waitcnt lgkmcnt(6)
	v_mfma_f32_16x16x32_bf16 v[114:117], v[170:173], v[158:161], v[114:117]
	v_mfma_f32_16x16x32_bf16 v[118:121], v[178:181], v[158:161], v[118:121]
	ds_read_b128 v[154:157], v216 offset:43008
	s_waitcnt lgkmcnt(6)
	v_mfma_f32_16x16x32_bf16 v[122:125], v[170:173], v[162:165], v[122:125]
	v_mfma_f32_16x16x32_bf16 v[126:129], v[178:181], v[162:165], v[126:129]
	v_add_u32_e32 v217, 0x80, v217
	v_add_u32_e32 v220, 0x800, v220
	v_add_u32_e32 v221, 0x800, v221
	s_lshr_b32 s3, s14, 4
	s_lshl_b32 s17, s15, 1
	s_add_u32 s3, s3, s17
	s_mul_i32 s17, s3, 0x8000
	s_add_u32 s8, s20, s17
	s_addc_u32 s9, s21, 0
	v_mov_b32_e32 v220, v222
	v_add_u32_e32 v221, 0x8000, v222
	ds_read_b128 v[158:161], v216 offset:45056
	s_waitcnt vmcnt(8) lgkmcnt(6)
	v_mfma_f32_16x16x32_bf16 v[2:5], v[196:199], v[134:137], v[2:5]
	global_load_dwordx4 v[166:169], v220, s[8:9]
	v_mfma_f32_16x16x32_bf16 v[6:9], v[204:207], v[134:137], v[6:9]
	global_load_dwordx4 v[170:173], v220, s[8:9] offset:1024
	ds_read_b128 v[162:165], v216 offset:47104
	s_waitcnt lgkmcnt(6)
	v_mfma_f32_16x16x32_bf16 v[10:13], v[196:199], v[138:141], v[10:13]
	global_load_dwordx4 v[174:177], v221, s[8:9]
	v_mfma_f32_16x16x32_bf16 v[14:17], v[204:207], v[138:141], v[14:17]
	global_load_dwordx4 v[178:181], v221, s[8:9] offset:1024
	ds_read_b128 v[134:137], v216 offset:49152
	s_waitcnt lgkmcnt(6)
	v_mfma_f32_16x16x32_bf16 v[18:21], v[196:199], v[142:145], v[18:21]
	v_mfma_f32_16x16x32_bf16 v[22:25], v[204:207], v[142:145], v[22:25]
	ds_read_b128 v[138:141], v216 offset:51200
	s_waitcnt lgkmcnt(6)
	v_mfma_f32_16x16x32_bf16 v[26:29], v[196:199], v[146:149], v[26:29]
	v_mfma_f32_16x16x32_bf16 v[30:33], v[204:207], v[146:149], v[30:33]
	ds_read_b128 v[142:145], v216 offset:53248
	s_waitcnt lgkmcnt(6)
	v_mfma_f32_16x16x32_bf16 v[34:37], v[196:199], v[150:153], v[34:37]
	v_mfma_f32_16x16x32_bf16 v[38:41], v[204:207], v[150:153], v[38:41]
	ds_read_b128 v[146:149], v216 offset:55296
	s_waitcnt lgkmcnt(6)
	v_mfma_f32_16x16x32_bf16 v[42:45], v[196:199], v[154:157], v[42:45]
	v_mfma_f32_16x16x32_bf16 v[46:49], v[204:207], v[154:157], v[46:49]
	ds_read_b128 v[150:153], v216 offset:57344
	s_waitcnt lgkmcnt(6)
	v_mfma_f32_16x16x32_bf16 v[50:53], v[196:199], v[158:161], v[50:53]
	v_mfma_f32_16x16x32_bf16 v[54:57], v[204:207], v[158:161], v[54:57]
	ds_read_b128 v[154:157], v216 offset:59392
	s_waitcnt lgkmcnt(6)
	v_mfma_f32_16x16x32_bf16 v[58:61], v[196:199], v[162:165], v[58:61]
	v_mfma_f32_16x16x32_bf16 v[62:65], v[204:207], v[162:165], v[62:65]
	ds_read_b128 v[158:161], v216 offset:61440
	s_waitcnt lgkmcnt(6)
	v_mfma_f32_16x16x32_bf16 v[66:69], v[196:199], v[134:137], v[66:69]
	v_mfma_f32_16x16x32_bf16 v[70:73], v[204:207], v[134:137], v[70:73]
	ds_read_b128 v[162:165], v216 offset:63488
	s_waitcnt lgkmcnt(6)
	v_mfma_f32_16x16x32_bf16 v[74:77], v[196:199], v[138:141], v[74:77]
	v_mfma_f32_16x16x32_bf16 v[78:81], v[204:207], v[138:141], v[78:81]
	ds_read_b128 v[134:137], v216 offset:33792
	s_waitcnt lgkmcnt(6)
	v_mfma_f32_16x16x32_bf16 v[82:85], v[196:199], v[142:145], v[82:85]
	v_mfma_f32_16x16x32_bf16 v[86:89], v[204:207], v[142:145], v[86:89]
	ds_read_b128 v[138:141], v216 offset:35840
	s_waitcnt lgkmcnt(6)
	v_mfma_f32_16x16x32_bf16 v[90:93], v[196:199], v[146:149], v[90:93]
	v_mfma_f32_16x16x32_bf16 v[94:97], v[204:207], v[146:149], v[94:97]
	ds_read_b128 v[142:145], v216 offset:37888
	s_waitcnt lgkmcnt(6)
	v_mfma_f32_16x16x32_bf16 v[98:101], v[196:199], v[150:153], v[98:101]
	v_mfma_f32_16x16x32_bf16 v[102:105], v[204:207], v[150:153], v[102:105]
	ds_read_b128 v[146:149], v216 offset:39936
	s_waitcnt lgkmcnt(6)
	v_mfma_f32_16x16x32_bf16 v[106:109], v[196:199], v[154:157], v[106:109]
	v_mfma_f32_16x16x32_bf16 v[110:113], v[204:207], v[154:157], v[110:113]
	ds_read_b128 v[150:153], v216 offset:41984
	s_waitcnt lgkmcnt(6)
	v_mfma_f32_16x16x32_bf16 v[114:117], v[196:199], v[158:161], v[114:117]
	v_mfma_f32_16x16x32_bf16 v[118:121], v[204:207], v[158:161], v[118:121]
	ds_read_b128 v[154:157], v216 offset:44032
	s_waitcnt lgkmcnt(6)
	v_mfma_f32_16x16x32_bf16 v[122:125], v[196:199], v[162:165], v[122:125]
	v_mfma_f32_16x16x32_bf16 v[126:129], v[204:207], v[162:165], v[126:129]
	ds_read_b128 v[158:161], v216 offset:46080
	s_waitcnt lgkmcnt(6)
	v_mfma_f32_16x16x32_bf16 v[2:5], v[200:203], v[134:137], v[2:5]
	v_mfma_f32_16x16x32_bf16 v[6:9], v[212:215], v[134:137], v[6:9]
	ds_read_b128 v[162:165], v216 offset:48128
	s_waitcnt lgkmcnt(6)
	v_mfma_f32_16x16x32_bf16 v[10:13], v[200:203], v[138:141], v[10:13]
	v_mfma_f32_16x16x32_bf16 v[14:17], v[212:215], v[138:141], v[14:17]
	ds_read_b128 v[134:137], v216 offset:50176
	s_waitcnt lgkmcnt(6)
	v_mfma_f32_16x16x32_bf16 v[18:21], v[200:203], v[142:145], v[18:21]
	v_mfma_f32_16x16x32_bf16 v[22:25], v[212:215], v[142:145], v[22:25]
	ds_read_b128 v[138:141], v216 offset:52224
	s_waitcnt lgkmcnt(6)
	v_mfma_f32_16x16x32_bf16 v[26:29], v[200:203], v[146:149], v[26:29]
	v_mfma_f32_16x16x32_bf16 v[30:33], v[212:215], v[146:149], v[30:33]
	ds_read_b128 v[142:145], v216 offset:54272
	s_waitcnt lgkmcnt(6)
	v_mfma_f32_16x16x32_bf16 v[34:37], v[200:203], v[150:153], v[34:37]
	v_mfma_f32_16x16x32_bf16 v[38:41], v[212:215], v[150:153], v[38:41]
	ds_read_b128 v[146:149], v216 offset:56320
	s_waitcnt lgkmcnt(6)
	v_mfma_f32_16x16x32_bf16 v[42:45], v[200:203], v[154:157], v[42:45]
	v_mfma_f32_16x16x32_bf16 v[46:49], v[212:215], v[154:157], v[46:49]
	ds_read_b128 v[150:153], v216 offset:58368
	s_waitcnt lgkmcnt(6)
	v_mfma_f32_16x16x32_bf16 v[50:53], v[200:203], v[158:161], v[50:53]
	v_mfma_f32_16x16x32_bf16 v[54:57], v[212:215], v[158:161], v[54:57]
	ds_read_b128 v[154:157], v216 offset:60416
	s_waitcnt lgkmcnt(6)
	v_mfma_f32_16x16x32_bf16 v[58:61], v[200:203], v[162:165], v[58:61]
	v_mfma_f32_16x16x32_bf16 v[62:65], v[212:215], v[162:165], v[62:65]
	ds_read_b128 v[158:161], v216 offset:62464
	s_waitcnt lgkmcnt(6)
	v_mfma_f32_16x16x32_bf16 v[66:69], v[200:203], v[134:137], v[66:69]
	v_mfma_f32_16x16x32_bf16 v[70:73], v[212:215], v[134:137], v[70:73]
	ds_read_b128 v[162:165], v216 offset:64512
	s_waitcnt vmcnt(4) lgkmcnt(0)
	s_barrier
	v_mfma_f32_16x16x32_bf16 v[74:77], v[200:203], v[138:141], v[74:77]
	s_add_u32 m0, s22, 0x8000
	v_mov_b32_e32 v223, v217
	global_load_lds_dwordx4 v223, s[6:7]
	v_mfma_f32_16x16x32_bf16 v[78:81], v[212:215], v[138:141], v[78:81]
	s_add_u32 m0, s22, 0x8400
	v_add_u32_e32 v224, 0x40, v217
	global_load_lds_dwordx4 v224, s[6:7]
	ds_read_b128 v[134:137], v216
	s_waitcnt lgkmcnt(6)
	v_mfma_f32_16x16x32_bf16 v[82:85], v[200:203], v[142:145], v[82:85]
	s_add_u32 m0, s22, 0x8800
	v_add_u32_e32 v223, 0x8000, v217
	global_load_lds_dwordx4 v223, s[6:7]
	v_mfma_f32_16x16x32_bf16 v[86:89], v[212:215], v[142:145], v[86:89]
	s_add_u32 m0, s22, 0x8c00
	v_add_u32_e32 v224, 0x8040, v217
	global_load_lds_dwordx4 v224, s[6:7]
	ds_read_b128 v[138:141], v216 offset:2048
	s_waitcnt lgkmcnt(6)
	v_mfma_f32_16x16x32_bf16 v[90:93], v[200:203], v[146:149], v[90:93]
	s_add_u32 m0, s22, 0x9000
	v_add_u32_e32 v223, 0x10000, v217
	global_load_lds_dwordx4 v223, s[6:7]
	v_mfma_f32_16x16x32_bf16 v[94:97], v[212:215], v[146:149], v[94:97]
	s_add_u32 m0, s22, 0x9400
	v_add_u32_e32 v224, 0x10040, v217
	global_load_lds_dwordx4 v224, s[6:7]
	ds_read_b128 v[142:145], v216 offset:4096
	s_waitcnt lgkmcnt(6)
	v_mfma_f32_16x16x32_bf16 v[98:101], v[200:203], v[150:153], v[98:101]
	s_add_u32 m0, s22, 0x9800
	v_add_u32_e32 v223, 0x18000, v217
	global_load_lds_dwordx4 v223, s[6:7]
	v_mfma_f32_16x16x32_bf16 v[102:105], v[212:215], v[150:153], v[102:105]
	s_add_u32 m0, s22, 0x9c00
	v_add_u32_e32 v224, 0x18040, v217
	global_load_lds_dwordx4 v224, s[6:7]
	ds_read_b128 v[146:149], v216 offset:6144
	s_waitcnt lgkmcnt(6)
	v_mfma_f32_16x16x32_bf16 v[106:109], v[200:203], v[154:157], v[106:109]
	v_mfma_f32_16x16x32_bf16 v[110:113], v[212:215], v[154:157], v[110:113]
	ds_read_b128 v[150:153], v216 offset:8192
	s_waitcnt lgkmcnt(6)
	v_mfma_f32_16x16x32_bf16 v[114:117], v[200:203], v[158:161], v[114:117]
	v_mfma_f32_16x16x32_bf16 v[118:121], v[212:215], v[158:161], v[118:121]
	ds_read_b128 v[154:157], v216 offset:10240
	s_waitcnt lgkmcnt(6)
	v_mfma_f32_16x16x32_bf16 v[122:125], v[200:203], v[162:165], v[122:125]
	v_mfma_f32_16x16x32_bf16 v[126:129], v[212:215], v[162:165], v[126:129]
	v_add_u32_e32 v217, 0x80, v217
	v_add_u32_e32 v220, 0x800, v220
	v_add_u32_e32 v221, 0x800, v221
	s_mov_b32 s16, 1
	s_branch .Lg256b_w1_epi
.Lg256b_w1_nonext:
	ds_read_b128 v[158:161], v216 offset:12288
	s_waitcnt vmcnt(8) lgkmcnt(6)
	v_mfma_f32_16x16x32_bf16 v[2:5], v[166:169], v[134:137], v[2:5]
	global_load_dwordx4 v[196:199], v220, s[8:9]
	v_mfma_f32_16x16x32_bf16 v[6:9], v[174:177], v[134:137], v[6:9]
	global_load_dwordx4 v[200:203], v220, s[8:9] offset:1024
	ds_read_b128 v[162:165], v216 offset:14336
	s_waitcnt lgkmcnt(6)
	v_mfma_f32_16x16x32_bf16 v[10:13], v[166:169], v[138:141], v[10:13]
	global_load_dwordx4 v[204:207], v221, s[8:9]
	v_mfma_f32_16x16x32_bf16 v[14:17], v[174:177], v[138:141], v[14:17]
	global_load_dwordx4 v[212:215], v221, s[8:9] offset:1024
	ds_read_b128 v[134:137], v216 offset:16384
	s_waitcnt lgkmcnt(6)
	v_mfma_f32_16x16x32_bf16 v[18:21], v[166:169], v[142:145], v[18:21]
	v_mfma_f32_16x16x32_bf16 v[22:25], v[174:177], v[142:145], v[22:25]
	ds_read_b128 v[138:141], v216 offset:18432
	s_waitcnt lgkmcnt(6)
	v_mfma_f32_16x16x32_bf16 v[26:29], v[166:169], v[146:149], v[26:29]
	v_mfma_f32_16x16x32_bf16 v[30:33], v[174:177], v[146:149], v[30:33]
	ds_read_b128 v[142:145], v216 offset:20480
	s_waitcnt lgkmcnt(6)
	v_mfma_f32_16x16x32_bf16 v[34:37], v[166:169], v[150:153], v[34:37]
	v_mfma_f32_16x16x32_bf16 v[38:41], v[174:177], v[150:153], v[38:41]
	ds_read_b128 v[146:149], v216 offset:22528
	s_waitcnt lgkmcnt(6)
	v_mfma_f32_16x16x32_bf16 v[42:45], v[166:169], v[154:157], v[42:45]
	v_mfma_f32_16x16x32_bf16 v[46:49], v[174:177], v[154:157], v[46:49]
	ds_read_b128 v[150:153], v216 offset:24576
	s_waitcnt lgkmcnt(6)
	v_mfma_f32_16x16x32_bf16 v[50:53], v[166:169], v[158:161], v[50:53]
	v_mfma_f32_16x16x32_bf16 v[54:57], v[174:177], v[158:161], v[54:57]
	ds_read_b128 v[154:157], v216 offset:26624
	s_waitcnt lgkmcnt(6)
	v_mfma_f32_16x16x32_bf16 v[58:61], v[166:169], v[162:165], v[58:61]
	v_mfma_f32_16x16x32_bf16 v[62:65], v[174:177], v[162:165], v[62:65]
	ds_read_b128 v[158:161], v216 offset:28672
	s_waitcnt lgkmcnt(6)
	v_mfma_f32_16x16x32_bf16 v[66:69], v[166:169], v[134:137], v[66:69]
	v_mfma_f32_16x16x32_bf16 v[70:73], v[174:177], v[134:137], v[70:73]
	ds_read_b128 v[162:165], v216 offset:30720
	s_waitcnt lgkmcnt(6)
	v_mfma_f32_16x16x32_bf16 v[74:77], v[166:169], v[138:141], v[74:77]
	v_mfma_f32_16x16x32_bf16 v[78:81], v[174:177], v[138:141], v[78:81]
	ds_read_b128 v[134:137], v216 offset:1024
	s_waitcnt lgkmcnt(6)
	v_mfma_f32_16x16x32_bf16 v[82:85], v[166:169], v[142:145], v[82:85]
	v_mfma_f32_16x16x32_bf16 v[86:89], v[174:177], v[142:145], v[86:89]
	ds_read_b128 v[138:141], v216 offset:3072
	s_waitcnt lgkmcnt(6)
	v_mfma_f32_16x16x32_bf16 v[90:93], v[166:169], v[146:149], v[90:93]
	v_mfma_f32_16x16x32_bf16 v[94:97], v[174:177], v[146:149], v[94:97]
	ds_read_b128 v[142:145], v216 offset:5120
	s_waitcnt lgkmcnt(6)
	v_mfma_f32_16x16x32_bf16 v[98:101], v[166:169], v[150:153], v[98:101]
	v_mfma_f32_16x16x32_bf16 v[102:105], v[174:177], v[150:153], v[102:105]
	ds_read_b128 v[146:149], v216 offset:7168
	s_waitcnt lgkmcnt(6)
	v_mfma_f32_16x16x32_bf16 v[106:109], v[166:169], v[154:157], v[106:109]
	v_mfma_f32_16x16x32_bf16 v[110:113], v[174:177], v[154:157], v[110:113]
	ds_read_b128 v[150:153], v216 offset:9216
	s_waitcnt lgkmcnt(6)
	v_mfma_f32_16x16x32_bf16 v[114:117], v[166:169], v[158:161], v[114:117]
	v_mfma_f32_16x16x32_bf16 v[118:121], v[174:177], v[158:161], v[118:121]
	ds_read_b128 v[154:157], v216 offset:11264
	s_waitcnt lgkmcnt(6)
	v_mfma_f32_16x16x32_bf16 v[122:125], v[166:169], v[162:165], v[122:125]
	v_mfma_f32_16x16x32_bf16 v[126:129], v[174:177], v[162:165], v[126:129]
	ds_read_b128 v[158:161], v216 offset:13312
	s_waitcnt lgkmcnt(6)
	v_mfma_f32_16x16x32_bf16 v[2:5], v[170:173], v[134:137], v[2:5]
	v_mfma_f32_16x16x32_bf16 v[6:9], v[178:181], v[134:137], v[6:9]
	ds_read_b128 v[162:165], v216 offset:15360
	s_waitcnt lgkmcnt(6)
	v_mfma_f32_16x16x32_bf16 v[10:13], v[170:173], v[138:141], v[10:13]
	v_mfma_f32_16x16x32_bf16 v[14:17], v[178:181], v[138:141], v[14:17]
	ds_read_b128 v[134:137], v216 offset:17408
	s_waitcnt lgkmcnt(6)
	v_mfma_f32_16x16x32_bf16 v[18:21], v[170:173], v[142:145], v[18:21]
	v_mfma_f32_16x16x32_bf16 v[22:25], v[178:181], v[142:145], v[22:25]
	ds_read_b128 v[138:141], v216 offset:19456
	s_waitcnt lgkmcnt(6)
	v_mfma_f32_16x16x32_bf16 v[26:29], v[170:173], v[146:149], v[26:29]
	v_mfma_f32_16x16x32_bf16 v[30:33], v[178:181], v[146:149], v[30:33]
	ds_read_b128 v[142:145], v216 offset:21504
	s_waitcnt lgkmcnt(6)
	v_mfma_f32_16x16x32_bf16 v[34:37], v[170:173], v[150:153], v[34:37]
	v_mfma_f32_16x16x32_bf16 v[38:41], v[178:181], v[150:153], v[38:41]
	ds_read_b128 v[146:149], v216 offset:23552
	s_waitcnt lgkmcnt(6)
	v_mfma_f32_16x16x32_bf16 v[42:45], v[170:173], v[154:157], v[42:45]
	v_mfma_f32_16x16x32_bf16 v[46:49], v[178:181], v[154:157], v[46:49]
	ds_read_b128 v[150:153], v216 offset:25600
	s_waitcnt lgkmcnt(6)
	v_mfma_f32_16x16x32_bf16 v[50:53], v[170:173], v[158:161], v[50:53]
	v_mfma_f32_16x16x32_bf16 v[54:57], v[178:181], v[158:161], v[54:57]
	ds_read_b128 v[154:157], v216 offset:27648
	s_waitcnt lgkmcnt(6)
	v_mfma_f32_16x16x32_bf16 v[58:61], v[170:173], v[162:165], v[58:61]
	v_mfma_f32_16x16x32_bf16 v[62:65], v[178:181], v[162:165], v[62:65]
	ds_read_b128 v[158:161], v216 offset:29696
	s_waitcnt lgkmcnt(6)
	v_mfma_f32_16x16x32_bf16 v[66:69], v[170:173], v[134:137], v[66:69]
	v_mfma_f32_16x16x32_bf16 v[70:73], v[178:181], v[134:137], v[70:73]
	ds_read_b128 v[162:165], v216 offset:31744
	s_waitcnt vmcnt(4) lgkmcnt(0)
	s_barrier
	v_mfma_f32_16x16x32_bf16 v[74:77], v[170:173], v[138:141], v[74:77]
	v_mfma_f32_16x16x32_bf16 v[78:81], v[178:181], v[138:141], v[78:81]
	ds_read_b128 v[134:137], v216 offset:32768
	s_waitcnt lgkmcnt(6)
	v_mfma_f32_16x16x32_bf16 v[82:85], v[170:173], v[142:145], v[82:85]
	v_mfma_f32_16x16x32_bf16 v[86:89], v[178:181], v[142:145], v[86:89]
	ds_read_b128 v[138:141], v216 offset:34816
	s_waitcnt lgkmcnt(6)
	v_mfma_f32_16x16x32_bf16 v[90:93], v[170:173], v[146:149], v[90:93]
	v_mfma_f32_16x16x32_bf16 v[94:97], v[178:181], v[146:149], v[94:97]
	ds_read_b128 v[142:145], v216 offset:36864
	s_waitcnt lgkmcnt(6)
	v_mfma_f32_16x16x32_bf16 v[98:101], v[170:173], v[150:153], v[98:101]
	v_mfma_f32_16x16x32_bf16 v[102:105], v[178:181], v[150:153], v[102:105]
	ds_read_b128 v[146:149], v216 offset:38912
	s_waitcnt lgkmcnt(6)
	v_mfma_f32_16x16x32_bf16 v[106:109], v[170:173], v[154:157], v[106:109]
	v_mfma_f32_16x16x32_bf16 v[110:113], v[178:181], v[154:157], v[110:113]
	ds_read_b128 v[150:153], v216 offset:40960
	s_waitcnt lgkmcnt(6)
	v_mfma_f32_16x16x32_bf16 v[114:117], v[170:173], v[158:161], v[114:117]
	v_mfma_f32_16x16x32_bf16 v[118:121], v[178:181], v[158:161], v[118:121]
	ds_read_b128 v[154:157], v216 offset:43008
	s_waitcnt lgkmcnt(6)
	v_mfma_f32_16x16x32_bf16 v[122:125], v[170:173], v[162:165], v[122:125]
	v_mfma_f32_16x16x32_bf16 v[126:129], v[178:181], v[162:165], v[126:129]
	v_add_u32_e32 v220, 0x800, v220
	v_add_u32_e32 v221, 0x800, v221
	ds_read_b128 v[158:161], v216 offset:45056
	s_waitcnt vmcnt(0) lgkmcnt(6)
	v_mfma_f32_16x16x32_bf16 v[2:5], v[196:199], v[134:137], v[2:5]
	v_mfma_f32_16x16x32_bf16 v[6:9], v[204:207], v[134:137], v[6:9]
	ds_read_b128 v[162:165], v216 offset:47104
	s_waitcnt lgkmcnt(6)
	v_mfma_f32_16x16x32_bf16 v[10:13], v[196:199], v[138:141], v[10:13]
	v_mfma_f32_16x16x32_bf16 v[14:17], v[204:207], v[138:141], v[14:17]
	ds_read_b128 v[134:137], v216 offset:49152
	s_waitcnt lgkmcnt(6)
	v_mfma_f32_16x16x32_bf16 v[18:21], v[196:199], v[142:145], v[18:21]
	v_mfma_f32_16x16x32_bf16 v[22:25], v[204:207], v[142:145], v[22:25]
	ds_read_b128 v[138:141], v216 offset:51200
	s_waitcnt lgkmcnt(6)
	v_mfma_f32_16x16x32_bf16 v[26:29], v[196:199], v[146:149], v[26:29]
	v_mfma_f32_16x16x32_bf16 v[30:33], v[204:207], v[146:149], v[30:33]
	ds_read_b128 v[142:145], v216 offset:53248
	s_waitcnt lgkmcnt(6)
	v_mfma_f32_16x16x32_bf16 v[34:37], v[196:199], v[150:153], v[34:37]
	v_mfma_f32_16x16x32_bf16 v[38:41], v[204:207], v[150:153], v[38:41]
	ds_read_b128 v[146:149], v216 offset:55296
	s_waitcnt lgkmcnt(6)
	v_mfma_f32_16x16x32_bf16 v[42:45], v[196:199], v[154:157], v[42:45]
	v_mfma_f32_16x16x32_bf16 v[46:49], v[204:207], v[154:157], v[46:49]
	ds_read_b128 v[150:153], v216 offset:57344
	s_waitcnt lgkmcnt(6)
	v_mfma_f32_16x16x32_bf16 v[50:53], v[196:199], v[158:161], v[50:53]
	v_mfma_f32_16x16x32_bf16 v[54:57], v[204:207], v[158:161], v[54:57]
	ds_read_b128 v[154:157], v216 offset:59392
	s_waitcnt lgkmcnt(6)
	v_mfma_f32_16x16x32_bf16 v[58:61], v[196:199], v[162:165], v[58:61]
	v_mfma_f32_16x16x32_bf16 v[62:65], v[204:207], v[162:165], v[62:65]
	ds_read_b128 v[158:161], v216 offset:61440
	s_waitcnt lgkmcnt(6)
	v_mfma_f32_16x16x32_bf16 v[66:69], v[196:199], v[134:137], v[66:69]
	v_mfma_f32_16x16x32_bf16 v[70:73], v[204:207], v[134:137], v[70:73]
	ds_read_b128 v[162:165], v216 offset:63488
	s_waitcnt lgkmcnt(6)
	v_mfma_f32_16x16x32_bf16 v[74:77], v[196:199], v[138:141], v[74:77]
	v_mfma_f32_16x16x32_bf16 v[78:81], v[204:207], v[138:141], v[78:81]
	ds_read_b128 v[134:137], v216 offset:33792
	s_waitcnt lgkmcnt(6)
	v_mfma_f32_16x16x32_bf16 v[82:85], v[196:199], v[142:145], v[82:85]
	v_mfma_f32_16x16x32_bf16 v[86:89], v[204:207], v[142:145], v[86:89]
	ds_read_b128 v[138:141], v216 offset:35840
	s_waitcnt lgkmcnt(6)
	v_mfma_f32_16x16x32_bf16 v[90:93], v[196:199], v[146:149], v[90:93]
	v_mfma_f32_16x16x32_bf16 v[94:97], v[204:207], v[146:149], v[94:97]
	ds_read_b128 v[142:145], v216 offset:37888
	s_waitcnt lgkmcnt(6)
	v_mfma_f32_16x16x32_bf16 v[98:101], v[196:199], v[150:153], v[98:101]
	v_mfma_f32_16x16x32_bf16 v[102:105], v[204:207], v[150:153], v[102:105]
	ds_read_b128 v[146:149], v216 offset:39936
	s_waitcnt lgkmcnt(6)
	v_mfma_f32_16x16x32_bf16 v[106:109], v[196:199], v[154:157], v[106:109]
	v_mfma_f32_16x16x32_bf16 v[110:113], v[204:207], v[154:157], v[110:113]
	ds_read_b128 v[150:153], v216 offset:41984
	s_waitcnt lgkmcnt(6)
	v_mfma_f32_16x16x32_bf16 v[114:117], v[196:199], v[158:161], v[114:117]
	v_mfma_f32_16x16x32_bf16 v[118:121], v[204:207], v[158:161], v[118:121]
	ds_read_b128 v[154:157], v216 offset:44032
	s_waitcnt lgkmcnt(6)
	v_mfma_f32_16x16x32_bf16 v[122:125], v[196:199], v[162:165], v[122:125]
	v_mfma_f32_16x16x32_bf16 v[126:129], v[204:207], v[162:165], v[126:129]
	ds_read_b128 v[158:161], v216 offset:46080
	s_waitcnt lgkmcnt(6)
	v_mfma_f32_16x16x32_bf16 v[2:5], v[200:203], v[134:137], v[2:5]
	v_mfma_f32_16x16x32_bf16 v[6:9], v[212:215], v[134:137], v[6:9]
	ds_read_b128 v[162:165], v216 offset:48128
	s_waitcnt lgkmcnt(6)
	v_mfma_f32_16x16x32_bf16 v[10:13], v[200:203], v[138:141], v[10:13]
	v_mfma_f32_16x16x32_bf16 v[14:17], v[212:215], v[138:141], v[14:17]
	ds_read_b128 v[134:137], v216 offset:50176
	s_waitcnt lgkmcnt(6)
	v_mfma_f32_16x16x32_bf16 v[18:21], v[200:203], v[142:145], v[18:21]
	v_mfma_f32_16x16x32_bf16 v[22:25], v[212:215], v[142:145], v[22:25]
	ds_read_b128 v[138:141], v216 offset:52224
	s_waitcnt lgkmcnt(6)
	v_mfma_f32_16x16x32_bf16 v[26:29], v[200:203], v[146:149], v[26:29]
	v_mfma_f32_16x16x32_bf16 v[30:33], v[212:215], v[146:149], v[30:33]
	ds_read_b128 v[142:145], v216 offset:54272
	s_waitcnt lgkmcnt(6)
	v_mfma_f32_16x16x32_bf16 v[34:37], v[200:203], v[150:153], v[34:37]
	v_mfma_f32_16x16x32_bf16 v[38:41], v[212:215], v[150:153], v[38:41]
	ds_read_b128 v[146:149], v216 offset:56320
	s_waitcnt lgkmcnt(6)
	v_mfma_f32_16x16x32_bf16 v[42:45], v[200:203], v[154:157], v[42:45]
	v_mfma_f32_16x16x32_bf16 v[46:49], v[212:215], v[154:157], v[46:49]
	ds_read_b128 v[150:153], v216 offset:58368
	s_waitcnt lgkmcnt(6)
	v_mfma_f32_16x16x32_bf16 v[50:53], v[200:203], v[158:161], v[50:53]
	v_mfma_f32_16x16x32_bf16 v[54:57], v[212:215], v[158:161], v[54:57]
	ds_read_b128 v[154:157], v216 offset:60416
	s_waitcnt lgkmcnt(6)
	v_mfma_f32_16x16x32_bf16 v[58:61], v[200:203], v[162:165], v[58:61]
	v_mfma_f32_16x16x32_bf16 v[62:65], v[212:215], v[162:165], v[62:65]
	ds_read_b128 v[158:161], v216 offset:62464
	s_waitcnt lgkmcnt(6)
	v_mfma_f32_16x16x32_bf16 v[66:69], v[200:203], v[134:137], v[66:69]
	v_mfma_f32_16x16x32_bf16 v[70:73], v[212:215], v[134:137], v[70:73]
	ds_read_b128 v[162:165], v216 offset:64512
	s_waitcnt vmcnt(0) lgkmcnt(0)
	s_barrier
	v_mfma_f32_16x16x32_bf16 v[74:77], v[200:203], v[138:141], v[74:77]
	v_mfma_f32_16x16x32_bf16 v[78:81], v[212:215], v[138:141], v[78:81]
	s_waitcnt lgkmcnt(6)
	v_mfma_f32_16x16x32_bf16 v[82:85], v[200:203], v[142:145], v[82:85]
	v_mfma_f32_16x16x32_bf16 v[86:89], v[212:215], v[142:145], v[86:89]
	s_waitcnt lgkmcnt(6)
	v_mfma_f32_16x16x32_bf16 v[90:93], v[200:203], v[146:149], v[90:93]
	v_mfma_f32_16x16x32_bf16 v[94:97], v[212:215], v[146:149], v[94:97]
	s_waitcnt lgkmcnt(6)
	v_mfma_f32_16x16x32_bf16 v[98:101], v[200:203], v[150:153], v[98:101]
	v_mfma_f32_16x16x32_bf16 v[102:105], v[212:215], v[150:153], v[102:105]
	s_waitcnt lgkmcnt(6)
	v_mfma_f32_16x16x32_bf16 v[106:109], v[200:203], v[154:157], v[106:109]
	v_mfma_f32_16x16x32_bf16 v[110:113], v[212:215], v[154:157], v[110:113]
	s_waitcnt lgkmcnt(6)
	v_mfma_f32_16x16x32_bf16 v[114:117], v[200:203], v[158:161], v[114:117]
	v_mfma_f32_16x16x32_bf16 v[118:121], v[212:215], v[158:161], v[118:121]
	s_waitcnt lgkmcnt(6)
	v_mfma_f32_16x16x32_bf16 v[122:125], v[200:203], v[162:165], v[122:125]
	v_mfma_f32_16x16x32_bf16 v[126:129], v[212:215], v[162:165], v[126:129]
	s_mov_b32 s16, 0
.Lg256b_w1_epi:
	v_max_f32_e32 v2, 0, v2
	v_max_f32_e32 v3, 0, v3
	v_max_f32_e32 v4, 0, v4
	v_max_f32_e32 v5, 0, v5
	v_pk_mul_f32 v[2:3], v[2:3], v[2:3]
	v_pk_mul_f32 v[4:5], v[4:5], v[4:5]
	v_cvt_pk_bf16_f32 v2, v2, v3
	v_cvt_pk_bf16_f32 v3, v4, v5
	global_store_dwordx2 v219, v[2:3], s[10:11]
	v_max_f32_e32 v6, 0, v6
	v_max_f32_e32 v7, 0, v7
	v_max_f32_e32 v8, 0, v8
	v_max_f32_e32 v9, 0, v9
	v_pk_mul_f32 v[6:7], v[6:7], v[6:7]
	v_pk_mul_f32 v[8:9], v[8:9], v[8:9]
	v_cvt_pk_bf16_f32 v6, v6, v7
	v_cvt_pk_bf16_f32 v7, v8, v9
	global_store_dwordx2 v219, v[6:7], s[10:11] offset:32
	v_add_u32_e32 v131, 0x20000, v219
	v_max_f32_e32 v10, 0, v10
	v_max_f32_e32 v11, 0, v11
	v_max_f32_e32 v12, 0, v12
	v_max_f32_e32 v13, 0, v13
	v_pk_mul_f32 v[10:11], v[10:11], v[10:11]
	v_pk_mul_f32 v[12:13], v[12:13], v[12:13]
	v_cvt_pk_bf16_f32 v10, v10, v11
	v_cvt_pk_bf16_f32 v11, v12, v13
	global_store_dwordx2 v131, v[10:11], s[10:11]
	v_max_f32_e32 v14, 0, v14
	v_max_f32_e32 v15, 0, v15
	v_max_f32_e32 v16, 0, v16
	v_max_f32_e32 v17, 0, v17
	v_pk_mul_f32 v[14:15], v[14:15], v[14:15]
	v_pk_mul_f32 v[16:17], v[16:17], v[16:17]
	v_cvt_pk_bf16_f32 v14, v14, v15
	v_cvt_pk_bf16_f32 v15, v16, v17
	global_store_dwordx2 v131, v[14:15], s[10:11] offset:32
	v_add_u32_e32 v131, 0x40000, v219
	v_max_f32_e32 v18, 0, v18
	v_max_f32_e32 v19, 0, v19
	v_max_f32_e32 v20, 0, v20
	v_max_f32_e32 v21, 0, v21
	v_pk_mul_f32 v[18:19], v[18:19], v[18:19]
	v_pk_mul_f32 v[20:21], v[20:21], v[20:21]
	v_cvt_pk_bf16_f32 v18, v18, v19
	v_cvt_pk_bf16_f32 v19, v20, v21
	global_store_dwordx2 v131, v[18:19], s[10:11]
	v_max_f32_e32 v22, 0, v22
	v_max_f32_e32 v23, 0, v23
	v_max_f32_e32 v24, 0, v24
	v_max_f32_e32 v25, 0, v25
	v_pk_mul_f32 v[22:23], v[22:23], v[22:23]
	v_pk_mul_f32 v[24:25], v[24:25], v[24:25]
	v_cvt_pk_bf16_f32 v22, v22, v23
	v_cvt_pk_bf16_f32 v23, v24, v25
	global_store_dwordx2 v131, v[22:23], s[10:11] offset:32
	v_add_u32_e32 v131, 0x60000, v219
	v_max_f32_e32 v26, 0, v26
	v_max_f32_e32 v27, 0, v27
	v_max_f32_e32 v28, 0, v28
	v_max_f32_e32 v29, 0, v29
	v_pk_mul_f32 v[26:27], v[26:27], v[26:27]
	v_pk_mul_f32 v[28:29], v[28:29], v[28:29]
	v_cvt_pk_bf16_f32 v26, v26, v27
	v_cvt_pk_bf16_f32 v27, v28, v29
	global_store_dwordx2 v131, v[26:27], s[10:11]
	v_max_f32_e32 v30, 0, v30
	v_max_f32_e32 v31, 0, v31
	v_max_f32_e32 v32, 0, v32
	v_max_f32_e32 v33, 0, v33
	v_pk_mul_f32 v[30:31], v[30:31], v[30:31]
	v_pk_mul_f32 v[32:33], v[32:33], v[32:33]
	v_cvt_pk_bf16_f32 v30, v30, v31
	v_cvt_pk_bf16_f32 v31, v32, v33
	global_store_dwordx2 v131, v[30:31], s[10:11] offset:32
	v_add_u32_e32 v131, 0x80000, v219
	v_max_f32_e32 v34, 0, v34
	v_max_f32_e32 v35, 0, v35
	v_max_f32_e32 v36, 0, v36
	v_max_f32_e32 v37, 0, v37
	v_pk_mul_f32 v[34:35], v[34:35], v[34:35]
	v_pk_mul_f32 v[36:37], v[36:37], v[36:37]
	v_cvt_pk_bf16_f32 v34, v34, v35
	v_cvt_pk_bf16_f32 v35, v36, v37
	global_store_dwordx2 v131, v[34:35], s[10:11]
	v_max_f32_e32 v38, 0, v38
	v_max_f32_e32 v39, 0, v39
	v_max_f32_e32 v40, 0, v40
	v_max_f32_e32 v41, 0, v41
	v_pk_mul_f32 v[38:39], v[38:39], v[38:39]
	v_pk_mul_f32 v[40:41], v[40:41], v[40:41]
	v_cvt_pk_bf16_f32 v38, v38, v39
	v_cvt_pk_bf16_f32 v39, v40, v41
	global_store_dwordx2 v131, v[38:39], s[10:11] offset:32
	v_add_u32_e32 v131, 0xa0000, v219
	v_max_f32_e32 v42, 0, v42
	v_max_f32_e32 v43, 0, v43
	v_max_f32_e32 v44, 0, v44
	v_max_f32_e32 v45, 0, v45
	v_pk_mul_f32 v[42:43], v[42:43], v[42:43]
	v_pk_mul_f32 v[44:45], v[44:45], v[44:45]
	v_cvt_pk_bf16_f32 v42, v42, v43
	v_cvt_pk_bf16_f32 v43, v44, v45
	global_store_dwordx2 v131, v[42:43], s[10:11]
	v_max_f32_e32 v46, 0, v46
	v_max_f32_e32 v47, 0, v47
	v_max_f32_e32 v48, 0, v48
	v_max_f32_e32 v49, 0, v49
	v_pk_mul_f32 v[46:47], v[46:47], v[46:47]
	v_pk_mul_f32 v[48:49], v[48:49], v[48:49]
	v_cvt_pk_bf16_f32 v46, v46, v47
	v_cvt_pk_bf16_f32 v47, v48, v49
	global_store_dwordx2 v131, v[46:47], s[10:11] offset:32
	v_add_u32_e32 v131, 0xc0000, v219
	v_max_f32_e32 v50, 0, v50
	v_max_f32_e32 v51, 0, v51
	v_max_f32_e32 v52, 0, v52
	v_max_f32_e32 v53, 0, v53
	v_pk_mul_f32 v[50:51], v[50:51], v[50:51]
	v_pk_mul_f32 v[52:53], v[52:53], v[52:53]
	v_cvt_pk_bf16_f32 v50, v50, v51
	v_cvt_pk_bf16_f32 v51, v52, v53
	global_store_dwordx2 v131, v[50:51], s[10:11]
	v_max_f32_e32 v54, 0, v54
	v_max_f32_e32 v55, 0, v55
	v_max_f32_e32 v56, 0, v56
	v_max_f32_e32 v57, 0, v57
	v_pk_mul_f32 v[54:55], v[54:55], v[54:55]
	v_pk_mul_f32 v[56:57], v[56:57], v[56:57]
	v_cvt_pk_bf16_f32 v54, v54, v55
	v_cvt_pk_bf16_f32 v55, v56, v57
	global_store_dwordx2 v131, v[54:55], s[10:11] offset:32
	v_add_u32_e32 v131, 0xe0000, v219
	v_max_f32_e32 v58, 0, v58
	v_max_f32_e32 v59, 0, v59
	v_max_f32_e32 v60, 0, v60
	v_max_f32_e32 v61, 0, v61
	v_pk_mul_f32 v[58:59], v[58:59], v[58:59]
	v_pk_mul_f32 v[60:61], v[60:61], v[60:61]
	v_cvt_pk_bf16_f32 v58, v58, v59
	v_cvt_pk_bf16_f32 v59, v60, v61
	global_store_dwordx2 v131, v[58:59], s[10:11]
	v_max_f32_e32 v62, 0, v62
	v_max_f32_e32 v63, 0, v63
	v_max_f32_e32 v64, 0, v64
	v_max_f32_e32 v65, 0, v65
	v_pk_mul_f32 v[62:63], v[62:63], v[62:63]
	v_pk_mul_f32 v[64:65], v[64:65], v[64:65]
	v_cvt_pk_bf16_f32 v62, v62, v63
	v_cvt_pk_bf16_f32 v63, v64, v65
	global_store_dwordx2 v131, v[62:63], s[10:11] offset:32
	v_add_u32_e32 v131, 0x100000, v219
	v_max_f32_e32 v66, 0, v66
	v_max_f32_e32 v67, 0, v67
	v_max_f32_e32 v68, 0, v68
	v_max_f32_e32 v69, 0, v69
	v_pk_mul_f32 v[66:67], v[66:67], v[66:67]
	v_pk_mul_f32 v[68:69], v[68:69], v[68:69]
	v_cvt_pk_bf16_f32 v66, v66, v67
	v_cvt_pk_bf16_f32 v67, v68, v69
	global_store_dwordx2 v131, v[66:67], s[10:11]
	v_max_f32_e32 v70, 0, v70
	v_max_f32_e32 v71, 0, v71
	v_max_f32_e32 v72, 0, v72
	v_max_f32_e32 v73, 0, v73
	v_pk_mul_f32 v[70:71], v[70:71], v[70:71]
	v_pk_mul_f32 v[72:73], v[72:73], v[72:73]
	v_cvt_pk_bf16_f32 v70, v70, v71
	v_cvt_pk_bf16_f32 v71, v72, v73
	global_store_dwordx2 v131, v[70:71], s[10:11] offset:32
	v_add_u32_e32 v131, 0x120000, v219
	v_max_f32_e32 v74, 0, v74
	v_max_f32_e32 v75, 0, v75
	v_max_f32_e32 v76, 0, v76
	v_max_f32_e32 v77, 0, v77
	v_pk_mul_f32 v[74:75], v[74:75], v[74:75]
	v_pk_mul_f32 v[76:77], v[76:77], v[76:77]
	v_cvt_pk_bf16_f32 v74, v74, v75
	v_cvt_pk_bf16_f32 v75, v76, v77
	global_store_dwordx2 v131, v[74:75], s[10:11]
	v_max_f32_e32 v78, 0, v78
	v_max_f32_e32 v79, 0, v79
	v_max_f32_e32 v80, 0, v80
	v_max_f32_e32 v81, 0, v81
	v_pk_mul_f32 v[78:79], v[78:79], v[78:79]
	v_pk_mul_f32 v[80:81], v[80:81], v[80:81]
	v_cvt_pk_bf16_f32 v78, v78, v79
	v_cvt_pk_bf16_f32 v79, v80, v81
	global_store_dwordx2 v131, v[78:79], s[10:11] offset:32
	v_add_u32_e32 v131, 0x140000, v219
	v_max_f32_e32 v82, 0, v82
	v_max_f32_e32 v83, 0, v83
	v_max_f32_e32 v84, 0, v84
	v_max_f32_e32 v85, 0, v85
	v_pk_mul_f32 v[82:83], v[82:83], v[82:83]
	v_pk_mul_f32 v[84:85], v[84:85], v[84:85]
	v_cvt_pk_bf16_f32 v82, v82, v83
	v_cvt_pk_bf16_f32 v83, v84, v85
	global_store_dwordx2 v131, v[82:83], s[10:11]
	v_max_f32_e32 v86, 0, v86
	v_max_f32_e32 v87, 0, v87
	v_max_f32_e32 v88, 0, v88
	v_max_f32_e32 v89, 0, v89
	v_pk_mul_f32 v[86:87], v[86:87], v[86:87]
	v_pk_mul_f32 v[88:89], v[88:89], v[88:89]
	v_cvt_pk_bf16_f32 v86, v86, v87
	v_cvt_pk_bf16_f32 v87, v88, v89
	global_store_dwordx2 v131, v[86:87], s[10:11] offset:32
	v_add_u32_e32 v131, 0x160000, v219
	v_max_f32_e32 v90, 0, v90
	v_max_f32_e32 v91, 0, v91
	v_max_f32_e32 v92, 0, v92
	v_max_f32_e32 v93, 0, v93
	v_pk_mul_f32 v[90:91], v[90:91], v[90:91]
	v_pk_mul_f32 v[92:93], v[92:93], v[92:93]
	v_cvt_pk_bf16_f32 v90, v90, v91
	v_cvt_pk_bf16_f32 v91, v92, v93
	global_store_dwordx2 v131, v[90:91], s[10:11]
	v_max_f32_e32 v94, 0, v94
	v_max_f32_e32 v95, 0, v95
	v_max_f32_e32 v96, 0, v96
	v_max_f32_e32 v97, 0, v97
	v_pk_mul_f32 v[94:95], v[94:95], v[94:95]
	v_pk_mul_f32 v[96:97], v[96:97], v[96:97]
	v_cvt_pk_bf16_f32 v94, v94, v95
	v_cvt_pk_bf16_f32 v95, v96, v97
	global_store_dwordx2 v131, v[94:95], s[10:11] offset:32
	v_add_u32_e32 v131, 0x180000, v219
	v_max_f32_e32 v98, 0, v98
	v_max_f32_e32 v99, 0, v99
	v_max_f32_e32 v100, 0, v100
	v_max_f32_e32 v101, 0, v101
	v_pk_mul_f32 v[98:99], v[98:99], v[98:99]
	v_pk_mul_f32 v[100:101], v[100:101], v[100:101]
	v_cvt_pk_bf16_f32 v98, v98, v99
	v_cvt_pk_bf16_f32 v99, v100, v101
	global_store_dwordx2 v131, v[98:99], s[10:11]
	v_max_f32_e32 v102, 0, v102
	v_max_f32_e32 v103, 0, v103
	v_max_f32_e32 v104, 0, v104
	v_max_f32_e32 v105, 0, v105
	v_pk_mul_f32 v[102:103], v[102:103], v[102:103]
	v_pk_mul_f32 v[104:105], v[104:105], v[104:105]
	v_cvt_pk_bf16_f32 v102, v102, v103
	v_cvt_pk_bf16_f32 v103, v104, v105
	global_store_dwordx2 v131, v[102:103], s[10:11] offset:32
	v_add_u32_e32 v131, 0x1a0000, v219
	v_max_f32_e32 v106, 0, v106
	v_max_f32_e32 v107, 0, v107
	v_max_f32_e32 v108, 0, v108
	v_max_f32_e32 v109, 0, v109
	v_pk_mul_f32 v[106:107], v[106:107], v[106:107]
	v_pk_mul_f32 v[108:109], v[108:109], v[108:109]
	v_cvt_pk_bf16_f32 v106, v106, v107
	v_cvt_pk_bf16_f32 v107, v108, v109
	global_store_dwordx2 v131, v[106:107], s[10:11]
	v_max_f32_e32 v110, 0, v110
	v_max_f32_e32 v111, 0, v111
	v_max_f32_e32 v112, 0, v112
	v_max_f32_e32 v113, 0, v113
	v_pk_mul_f32 v[110:111], v[110:111], v[110:111]
	v_pk_mul_f32 v[112:113], v[112:113], v[112:113]
	v_cvt_pk_bf16_f32 v110, v110, v111
	v_cvt_pk_bf16_f32 v111, v112, v113
	global_store_dwordx2 v131, v[110:111], s[10:11] offset:32
	v_add_u32_e32 v131, 0x1c0000, v219
	v_max_f32_e32 v114, 0, v114
	v_max_f32_e32 v115, 0, v115
	v_max_f32_e32 v116, 0, v116
	v_max_f32_e32 v117, 0, v117
	v_pk_mul_f32 v[114:115], v[114:115], v[114:115]
	v_pk_mul_f32 v[116:117], v[116:117], v[116:117]
	v_cvt_pk_bf16_f32 v114, v114, v115
	v_cvt_pk_bf16_f32 v115, v116, v117
	global_store_dwordx2 v131, v[114:115], s[10:11]
	v_max_f32_e32 v118, 0, v118
	v_max_f32_e32 v119, 0, v119
	v_max_f32_e32 v120, 0, v120
	v_max_f32_e32 v121, 0, v121
	v_pk_mul_f32 v[118:119], v[118:119], v[118:119]
	v_pk_mul_f32 v[120:121], v[120:121], v[120:121]
	v_cvt_pk_bf16_f32 v118, v118, v119
	v_cvt_pk_bf16_f32 v119, v120, v121
	global_store_dwordx2 v131, v[118:119], s[10:11] offset:32
	v_add_u32_e32 v131, 0x1e0000, v219
	v_max_f32_e32 v122, 0, v122
	v_max_f32_e32 v123, 0, v123
	v_max_f32_e32 v124, 0, v124
	v_max_f32_e32 v125, 0, v125
	v_pk_mul_f32 v[122:123], v[122:123], v[122:123]
	v_pk_mul_f32 v[124:125], v[124:125], v[124:125]
	v_cvt_pk_bf16_f32 v122, v122, v123
	v_cvt_pk_bf16_f32 v123, v124, v125
	global_store_dwordx2 v131, v[122:123], s[10:11]
	v_max_f32_e32 v126, 0, v126
	v_max_f32_e32 v127, 0, v127
	v_max_f32_e32 v128, 0, v128
	v_max_f32_e32 v129, 0, v129
	v_pk_mul_f32 v[126:127], v[126:127], v[126:127]
	v_pk_mul_f32 v[128:129], v[128:129], v[128:129]
	v_cvt_pk_bf16_f32 v126, v126, v127
	v_cvt_pk_bf16_f32 v127, v128, v129
	global_store_dwordx2 v131, v[126:127], s[10:11] offset:32
	s_cmp_lg_u32 s16, 0
	s_cbranch_scc1 .Lg256b_w1_tile

.LBB0_853:
	s_load_dwordx2 s[6:7], s[0:1], 0x130
	s_add_i32 s25, s24, 0xfffff800
	s_waitcnt lgkmcnt(0)
	s_cmp_lt_u32 s25, 2192
	s_cbranch_scc1 .Lcv_skip_w1
	s_cmp_lt_u32 s25, 3216
	s_cbranch_scc1 .Lcv_do_w1

.Lcv_do_w1:
	s_load_dwordx2 s[20:21], s[0:1], 0x118
	s_sub_u32 s25, s25, 2192
	s_and_b32 s26, s25, 63
	s_lshr_b32 s25, s25, 6
	s_mov_b32 s18, 4096
	s_mov_b32 s19, 32
	s_mov_b32 s28, 0x1b27800
	s_mov_b32 s29, 0
	s_mul_i32 s27, s62, 0x1000000
	s_waitcnt lgkmcnt(0)
	s_add_u32 s20, s20, s27
	s_addc_u32 s21, s21, 0
	s_branch .Lcv_tile
.Lcv_tile:
	s_lshl_b32 s25, s25, 6
	s_lshl_b32 s26, s26, 6
	s_mul_i32 s27, s25, s18
	s_lshl_b32 s27, s27, 2
	s_add_u32 s20, s20, s27
	s_addc_u32 s21, s21, 0
	v_mov_b32_e32 v2, v133
	v_lshrrev_b32_e32 v3, 4, v2
	v_and_b32_e32 v4, 15, v2
	v_lshlrev_b32_e32 v4, 2, v4
	v_add_u32_e32 v5, s26, v4
	s_sub_u32 s27, s18, 4
	v_min_u32_e32 v5, s27, v5
	v_mul_lo_u32 v6, v3, s18
	v_add_lshl_u32 v6, v6, v5, 2
	s_lshl_b32 s27, s18, 6
	global_load_dwordx4 v[8:11], v6, s[20:21]
	v_add_u32_e32 v6, s27, v6
	global_load_dwordx4 v[12:15], v6, s[20:21]
	v_add_u32_e32 v6, s27, v6
	global_load_dwordx4 v[16:19], v6, s[20:21]
	v_add_u32_e32 v6, s27, v6
	global_load_dwordx4 v[20:23], v6, s[20:21]
	v_mul_u32_u24_e32 v7, 65, v3
	v_add_lshl_u32 v7, v7, v4, 2
	s_waitcnt vmcnt(0)
	ds_write_b32 v7, v8
	ds_write_b32 v7, v9 offset:4
	ds_write_b32 v7, v10 offset:8
	ds_write_b32 v7, v11 offset:12
	ds_write_b32 v7, v12 offset:4160
	ds_write_b32 v7, v13 offset:4164
	ds_write_b32 v7, v14 offset:4168
	ds_write_b32 v7, v15 offset:4172
	ds_write_b32 v7, v16 offset:8320
	ds_write_b32 v7, v17 offset:8324
	ds_write_b32 v7, v18 offset:8328
	ds_write_b32 v7, v19 offset:8332
	ds_write_b32 v7, v20 offset:12480
	ds_write_b32 v7, v21 offset:12484
	ds_write_b32 v7, v22 offset:12488
	ds_write_b32 v7, v23 offset:12492
	s_waitcnt lgkmcnt(0)
	s_barrier
	v_and_b32_e32 v3, 63, v2
	v_lshrrev_b32_e32 v4, 6, v2
	v_and_b32_e32 v5, 15, v3
	v_lshrrev_b32_e32 v6, 4, v3
	v_readfirstlane_b32 s27, v4
	v_mul_u32_u24_e32 v7, 520, v6
	v_lshl_add_u32 v7, v4, 4, v7
	v_add_lshl_u32 v7, v7, v5, 2
	s_lshr_b32 s26, s26, 4
	s_add_u32 s26, s26, s27
	s_lshr_b32 s27, s18, 4
	s_cmp_ge_u32 s26, s27
	s_cbranch_scc1 .Lcv_end
	s_cmp_eq_u32 s29, 0
	s_cbranch_scc1 .Lcv_noperm
	s_cmp_lt_u32 s26, 128
	s_cbranch_scc1 .Lcv_noperm
	s_cmp_eq_u32 s26, 128
	s_cselect_b32 s27, 161, s26
	s_sub_u32 s26, s27, 1
.Lcv_noperm:
	s_mul_i32 s26, s26, s19
	s_lshr_b32 s25, s25, 5
	s_add_u32 s26, s26, s25
	s_lshl_b32 s26, s26, 10
	s_add_u32 s26, s26, s28
	v_lshlrev_b32_e32 v8, 4, v3
	v_add_u32_e32 v8, s26, v8
	ds_read_b32 v10, v7 offset:0
	ds_read_b32 v11, v7 offset:260
	ds_read_b32 v12, v7 offset:520
	ds_read_b32 v13, v7 offset:780
	ds_read_b32 v14, v7 offset:1040
	ds_read_b32 v15, v7 offset:1300
	ds_read_b32 v16, v7 offset:1560
	ds_read_b32 v17, v7 offset:1820
	ds_read_b32 v18, v7 offset:8320
	ds_read_b32 v19, v7 offset:8580
	ds_read_b32 v20, v7 offset:8840
	ds_read_b32 v21, v7 offset:9100
	ds_read_b32 v22, v7 offset:9360
	ds_read_b32 v23, v7 offset:9620
	ds_read_b32 v24, v7 offset:9880
	ds_read_b32 v25, v7 offset:10140
	s_waitcnt lgkmcnt(0)
	v_cvt_pk_bf16_f32 v26, v10, v11
	v_cvt_pk_bf16_f32 v27, v12, v13
	v_cvt_pk_bf16_f32 v28, v14, v15
	v_cvt_pk_bf16_f32 v29, v16, v17
	global_store_dwordx4 v8, v[26:29], s[6:7]
	s_nop 1
	v_cvt_pk_bf16_f32 v26, v18, v19
	v_cvt_pk_bf16_f32 v27, v20, v21
	v_cvt_pk_bf16_f32 v28, v22, v23
	v_cvt_pk_bf16_f32 v29, v24, v25
	global_store_dwordx4 v8, v[26:29], s[6:7] offset:1024
.Lcv_end:
	s_barrier
	s_branch .LBB0_850
.Lcv_orig:
	s_cmpk_gt_u32 s25, 0x28f
	s_cbranch_scc0 .LBB0_861
	s_cmpk_gt_u32 s25, 0x68f
	s_cbranch_scc0 .LBB0_862
	s_cmpk_gt_u32 s25, 0x78f
	s_cbranch_scc0 .LBB0_863
	s_cmpk_gt_u32 s25, 0x88f
	s_cbranch_scc0 .LBB0_864
	s_cmpk_gt_u32 s25, 0xc8f
	s_cbranch_scc0 .LBB0_865
	s_cmpk_gt_u32 s25, 0x108f
	s_mov_b64 s[20:21], -1
	s_cbranch_scc1 .LBB0_866
	s_mov_b64 s[18:19], 0
	s_andn2_b64 vcc, exec, s[20:21]
	s_mov_b64 s[20:21], 0
	s_cbranch_vccz .LBB0_870
